# MFMA order within 16-blocks grouped by shared B-fragment operand (src0)
# baseline (speedup 1.0000x reference)
.LBB0_139:
	s_add_u32 s22, s18, 0xfff00080
	s_addc_u32 s23, s19, -1
	s_add_i32 s49, 0, 0x10000
	s_cmp_eq_u32 s48, 60
	s_cselect_b32 s25, s9, s23
	s_cselect_b32 s24, s44, s22
	s_cselect_b32 s23, s7, s47
	s_cselect_b32 s22, s45, s46
	s_add_i32 s52, 0, 0x14000
	v_add_u32_e32 v156, s49, v145
	v_add_u32_e32 v172, s52, v145
	ds_read_b128 v[140:143], v156
	ds_read_b128 v[148:151], v156 offset:1024
	ds_read_b128 v[152:155], v156 offset:2048
	ds_read_b128 v[156:159], v156 offset:3072
	ds_read_b128 v[160:163], v172
	ds_read_b128 v[164:167], v172 offset:1024
	ds_read_b128 v[168:171], v172 offset:2048
	ds_read_b128 v[190:193], v172 offset:3072
	v_lshl_add_u64 v[172:173], s[18:19], 0, v[136:137]
	s_add_i32 m0, s31, 0xc000
	ds_read_b128 v[194:197], v147
	ds_read_b128 v[198:201], v147 offset:1024
	ds_read_b128 v[202:205], v147 offset:2048
	ds_read_b128 v[206:209], v147 offset:3072
	ds_read_b128 v[228:231], v147 offset:4096
	ds_read_b128 v[232:235], v147 offset:5120
	ds_read_b128 v[236:239], v147 offset:6144
	ds_read_b128 v[240:243], v147 offset:7168
	global_load_lds_dwordx4 v[172:173], off
	v_lshl_add_u64 v[172:173], s[18:19], 0, v[138:139]
	s_add_i32 m0, s31, 0xe000
	s_nop 0
	global_load_lds_dwordx4 v[172:173], off
	s_waitcnt vmcnt(8)
	s_waitcnt lgkmcnt(0)
	s_barrier
	s_setprio 1
	s_waitcnt lgkmcnt(0)
	v_mfma_f32_16x16x32_bf16 v[126:129], v[140:143], v[194:197], v[126:129]
	v_mfma_f32_16x16x32_bf16 v[118:121], v[140:143], v[202:205], v[118:121]
	v_mfma_f32_16x16x32_bf16 v[102:105], v[140:143], v[228:231], v[102:105]
	v_mfma_f32_16x16x32_bf16 v[86:89], v[140:143], v[236:239], v[86:89]
	v_mfma_f32_16x16x32_bf16 v[122:125], v[152:155], v[194:197], v[122:125]
	v_mfma_f32_16x16x32_bf16 v[110:113], v[152:155], v[202:205], v[110:113]
	v_mfma_f32_16x16x32_bf16 v[94:97], v[152:155], v[228:231], v[94:97]
	v_mfma_f32_16x16x32_bf16 v[78:81], v[152:155], v[236:239], v[78:81]
	v_mfma_f32_16x16x32_bf16 v[126:129], v[148:151], v[198:201], v[126:129]
	v_mfma_f32_16x16x32_bf16 v[118:121], v[148:151], v[206:209], v[118:121]
	v_mfma_f32_16x16x32_bf16 v[102:105], v[148:151], v[232:235], v[102:105]
	v_mfma_f32_16x16x32_bf16 v[86:89], v[148:151], v[240:243], v[86:89]
	v_mfma_f32_16x16x32_bf16 v[122:125], v[156:159], v[198:201], v[122:125]
	v_mfma_f32_16x16x32_bf16 v[110:113], v[156:159], v[206:209], v[110:113]
	v_mfma_f32_16x16x32_bf16 v[94:97], v[156:159], v[232:235], v[94:97]
	v_mfma_f32_16x16x32_bf16 v[78:81], v[156:159], v[240:243], v[78:81]
	s_setprio 0
	s_setprio 1
	v_mfma_f32_16x16x32_bf16 v[114:117], v[160:163], v[194:197], v[114:117]
	v_mfma_f32_16x16x32_bf16 v[98:101], v[160:163], v[202:205], v[98:101]
	v_mfma_f32_16x16x32_bf16 v[82:85], v[160:163], v[228:231], v[82:85]
	v_mfma_f32_16x16x32_bf16 v[70:73], v[160:163], v[236:239], v[70:73]
	v_mfma_f32_16x16x32_bf16 v[106:109], v[168:171], v[194:197], v[106:109]
	v_mfma_f32_16x16x32_bf16 v[90:93], v[168:171], v[202:205], v[90:93]
	v_mfma_f32_16x16x32_bf16 v[74:77], v[168:171], v[228:231], v[74:77]
	v_mfma_f32_16x16x32_bf16 v[66:69], v[168:171], v[236:239], v[66:69]
	v_mfma_f32_16x16x32_bf16 v[114:117], v[164:167], v[198:201], v[114:117]
	v_mfma_f32_16x16x32_bf16 v[98:101], v[164:167], v[206:209], v[98:101]
	v_mfma_f32_16x16x32_bf16 v[82:85], v[164:167], v[232:235], v[82:85]
	v_mfma_f32_16x16x32_bf16 v[70:73], v[164:167], v[240:243], v[70:73]
	v_mfma_f32_16x16x32_bf16 v[106:109], v[190:193], v[198:201], v[106:109]
	v_mfma_f32_16x16x32_bf16 v[90:93], v[190:193], v[206:209], v[90:93]
	v_mfma_f32_16x16x32_bf16 v[74:77], v[190:193], v[232:235], v[74:77]
	v_mfma_f32_16x16x32_bf16 v[66:69], v[190:193], v[240:243], v[66:69]
	s_setprio 0
	s_barrier
	s_add_i32 s49, s49, s26
	v_lshl_add_u64 v[172:173], s[22:23], 0, v[0:1]
	s_mov_b32 m0, s49
	ds_read_b128 v[194:197], v147 offset:16384
	ds_read_b128 v[198:201], v147 offset:17408
	ds_read_b128 v[202:205], v147 offset:18432
	ds_read_b128 v[206:209], v147 offset:19456
	ds_read_b128 v[228:231], v147 offset:20480
	ds_read_b128 v[232:235], v147 offset:21504
	ds_read_b128 v[236:239], v147 offset:22528
	ds_read_b128 v[240:243], v147 offset:23552
	global_load_lds_dwordx4 v[172:173], off
	s_add_i32 m0, s49, 0x2000
	s_add_u32 s50, s22, 0x100000
	v_lshl_add_u64 v[178:179], s[22:23], 0, v[130:131]
	s_addc_u32 s51, s23, 0
	s_add_i32 s49, s52, s26
	global_load_lds_dwordx4 v[178:179], off
	v_lshl_add_u64 v[180:181], s[50:51], 0, v[0:1]
	s_mov_b32 m0, s49
	v_lshl_add_u64 v[210:211], s[24:25], 0, v[132:133]
	global_load_lds_dwordx4 v[180:181], off
	v_lshl_add_u64 v[180:181], s[50:51], 0, v[130:131]
	s_add_i32 m0, s49, 0x2000
	s_nop 0
	global_load_lds_dwordx4 v[180:181], off
	v_lshl_add_u64 v[180:181], s[24:25], 0, v[134:135]
	s_mov_b32 m0, s31
	s_nop 0
	global_load_lds_dwordx4 v[180:181], off
	s_mov_b32 m0, s36
	s_nop 0
	global_load_lds_dwordx4 v[210:211], off
	s_waitcnt vmcnt(8)
	s_waitcnt lgkmcnt(0)
	s_barrier
	s_setprio 1
	s_waitcnt lgkmcnt(0)
	v_mfma_f32_16x16x32_bf16 v[62:65], v[140:143], v[194:197], v[62:65]
	v_mfma_f32_16x16x32_bf16 v[54:57], v[140:143], v[202:205], v[54:57]
	v_mfma_f32_16x16x32_bf16 v[38:41], v[140:143], v[228:231], v[38:41]
	v_mfma_f32_16x16x32_bf16 v[22:25], v[140:143], v[236:239], v[22:25]
	v_mfma_f32_16x16x32_bf16 v[58:61], v[152:155], v[194:197], v[58:61]
	v_mfma_f32_16x16x32_bf16 v[46:49], v[152:155], v[202:205], v[46:49]
	v_mfma_f32_16x16x32_bf16 v[30:33], v[152:155], v[228:231], v[30:33]
	v_mfma_f32_16x16x32_bf16 v[14:17], v[152:155], v[236:239], v[14:17]
	v_mfma_f32_16x16x32_bf16 v[62:65], v[148:151], v[198:201], v[62:65]
	v_mfma_f32_16x16x32_bf16 v[54:57], v[148:151], v[206:209], v[54:57]
	v_mfma_f32_16x16x32_bf16 v[38:41], v[148:151], v[232:235], v[38:41]
	v_mfma_f32_16x16x32_bf16 v[22:25], v[148:151], v[240:243], v[22:25]
	v_mfma_f32_16x16x32_bf16 v[58:61], v[156:159], v[198:201], v[58:61]
	v_mfma_f32_16x16x32_bf16 v[46:49], v[156:159], v[206:209], v[46:49]
	v_mfma_f32_16x16x32_bf16 v[30:33], v[156:159], v[232:235], v[30:33]
	v_mfma_f32_16x16x32_bf16 v[14:17], v[156:159], v[240:243], v[14:17]
	s_setprio 0
	s_setprio 1
	v_mfma_f32_16x16x32_bf16 v[50:53], v[160:163], v[194:197], v[50:53]
	v_mfma_f32_16x16x32_bf16 v[34:37], v[160:163], v[202:205], v[34:37]
	v_mfma_f32_16x16x32_bf16 v[18:21], v[160:163], v[228:231], v[18:21]
	v_mfma_f32_16x16x32_bf16 v[6:9], v[160:163], v[236:239], v[6:9]
	v_mfma_f32_16x16x32_bf16 v[42:45], v[168:171], v[194:197], v[42:45]
	v_mfma_f32_16x16x32_bf16 v[26:29], v[168:171], v[202:205], v[26:29]
	v_mfma_f32_16x16x32_bf16 v[10:13], v[168:171], v[228:231], v[10:13]
	v_mfma_f32_16x16x32_bf16 v[2:5], v[168:171], v[236:239], v[2:5]
	v_mfma_f32_16x16x32_bf16 v[50:53], v[164:167], v[198:201], v[50:53]
	v_mfma_f32_16x16x32_bf16 v[34:37], v[164:167], v[206:209], v[34:37]
	v_mfma_f32_16x16x32_bf16 v[18:21], v[164:167], v[232:235], v[18:21]
	v_mfma_f32_16x16x32_bf16 v[6:9], v[164:167], v[240:243], v[6:9]
	v_mfma_f32_16x16x32_bf16 v[42:45], v[190:193], v[198:201], v[42:45]
	v_mfma_f32_16x16x32_bf16 v[26:29], v[190:193], v[206:209], v[26:29]
	v_mfma_f32_16x16x32_bf16 v[10:13], v[190:193], v[232:235], v[10:13]
	v_mfma_f32_16x16x32_bf16 v[2:5], v[190:193], v[240:243], v[2:5]
	s_setprio 0
	s_barrier
	s_add_i32 s49, 0, 0x18000
	s_add_i32 s50, 0, 0x1c000
	v_add_u32_e32 v156, s49, v145
	v_add_u32_e32 v175, s50, v145
	ds_read_b128 v[140:143], v156
	ds_read_b128 v[148:151], v156 offset:1024
	ds_read_b128 v[152:155], v156 offset:2048
	ds_read_b128 v[156:159], v156 offset:3072
	ds_read_b128 v[160:163], v175
	ds_read_b128 v[164:167], v175 offset:1024
	ds_read_b128 v[168:171], v175 offset:2048
	ds_read_b128 v[190:193], v175 offset:3072
	s_add_u32 s24, s24, 0x100000
	s_addc_u32 s25, s25, 0
	s_mov_b32 m0, s37
	v_lshl_add_u64 v[244:245], s[24:25], 0, v[134:135]
	ds_read_b128 v[194:197], v147 offset:32768
	ds_read_b128 v[198:201], v147 offset:33792
	ds_read_b128 v[202:205], v147 offset:34816
	ds_read_b128 v[206:209], v147 offset:35840
	ds_read_b128 v[228:231], v147 offset:36864
	ds_read_b128 v[232:235], v147 offset:37888
	ds_read_b128 v[236:239], v147 offset:38912
	ds_read_b128 v[240:243], v147 offset:39936
	global_load_lds_dwordx4 v[244:245], off
	v_lshl_add_u64 v[244:245], s[24:25], 0, v[132:133]
	s_mov_b32 m0, s38
	s_nop 0
	global_load_lds_dwordx4 v[244:245], off
	s_waitcnt vmcnt(8)
	s_waitcnt lgkmcnt(0)
	s_barrier
	s_setprio 1
	s_waitcnt lgkmcnt(0)
	v_mfma_f32_16x16x32_bf16 v[126:129], v[140:143], v[194:197], v[126:129]
	v_mfma_f32_16x16x32_bf16 v[118:121], v[140:143], v[202:205], v[118:121]
	v_mfma_f32_16x16x32_bf16 v[102:105], v[140:143], v[228:231], v[102:105]
	v_mfma_f32_16x16x32_bf16 v[86:89], v[140:143], v[236:239], v[86:89]
	v_mfma_f32_16x16x32_bf16 v[122:125], v[152:155], v[194:197], v[122:125]
	v_mfma_f32_16x16x32_bf16 v[110:113], v[152:155], v[202:205], v[110:113]
	v_mfma_f32_16x16x32_bf16 v[94:97], v[152:155], v[228:231], v[94:97]
	v_mfma_f32_16x16x32_bf16 v[78:81], v[152:155], v[236:239], v[78:81]
	v_mfma_f32_16x16x32_bf16 v[126:129], v[148:151], v[198:201], v[126:129]
	v_mfma_f32_16x16x32_bf16 v[118:121], v[148:151], v[206:209], v[118:121]
	v_mfma_f32_16x16x32_bf16 v[102:105], v[148:151], v[232:235], v[102:105]
	v_mfma_f32_16x16x32_bf16 v[86:89], v[148:151], v[240:243], v[86:89]
	v_mfma_f32_16x16x32_bf16 v[122:125], v[156:159], v[198:201], v[122:125]
	v_mfma_f32_16x16x32_bf16 v[110:113], v[156:159], v[206:209], v[110:113]
	v_mfma_f32_16x16x32_bf16 v[94:97], v[156:159], v[232:235], v[94:97]
	v_mfma_f32_16x16x32_bf16 v[78:81], v[156:159], v[240:243], v[78:81]
	s_setprio 0
	s_setprio 1
	v_mfma_f32_16x16x32_bf16 v[114:117], v[160:163], v[194:197], v[114:117]
	v_mfma_f32_16x16x32_bf16 v[98:101], v[160:163], v[202:205], v[98:101]
	v_mfma_f32_16x16x32_bf16 v[82:85], v[160:163], v[228:231], v[82:85]
	v_mfma_f32_16x16x32_bf16 v[70:73], v[160:163], v[236:239], v[70:73]
	v_mfma_f32_16x16x32_bf16 v[106:109], v[168:171], v[194:197], v[106:109]
	v_mfma_f32_16x16x32_bf16 v[90:93], v[168:171], v[202:205], v[90:93]
	v_mfma_f32_16x16x32_bf16 v[74:77], v[168:171], v[228:231], v[74:77]
	v_mfma_f32_16x16x32_bf16 v[66:69], v[168:171], v[236:239], v[66:69]
	v_mfma_f32_16x16x32_bf16 v[114:117], v[164:167], v[198:201], v[114:117]
	v_mfma_f32_16x16x32_bf16 v[98:101], v[164:167], v[206:209], v[98:101]
	v_mfma_f32_16x16x32_bf16 v[82:85], v[164:167], v[232:235], v[82:85]
	v_mfma_f32_16x16x32_bf16 v[70:73], v[164:167], v[240:243], v[70:73]
	v_mfma_f32_16x16x32_bf16 v[106:109], v[190:193], v[198:201], v[106:109]
	v_mfma_f32_16x16x32_bf16 v[90:93], v[190:193], v[206:209], v[90:93]
	v_mfma_f32_16x16x32_bf16 v[74:77], v[190:193], v[232:235], v[74:77]
	v_mfma_f32_16x16x32_bf16 v[66:69], v[190:193], v[240:243], v[66:69]
	s_setprio 0
	s_barrier
	s_add_i32 s24, s49, s26
	v_lshl_add_u64 v[172:173], v[172:173], 0, s[34:35]
	s_mov_b32 m0, s24
	ds_read_b128 v[194:197], v147 offset:49152
	ds_read_b128 v[198:201], v147 offset:50176
	ds_read_b128 v[202:205], v147 offset:51200
	ds_read_b128 v[206:209], v147 offset:52224
	ds_read_b128 v[228:231], v147 offset:53248
	ds_read_b128 v[232:235], v147 offset:54272
	ds_read_b128 v[236:239], v147 offset:55296
	ds_read_b128 v[240:243], v147 offset:56320
	global_load_lds_dwordx4 v[172:173], off
	s_add_i32 m0, s24, 0x2000
	s_add_u32 s22, s22, 0x100080
	v_lshl_add_u64 v[172:173], v[178:179], 0, s[34:35]
	s_addc_u32 s23, s23, 0
	s_add_i32 s24, s50, s26
	global_load_lds_dwordx4 v[172:173], off
	v_lshl_add_u64 v[172:173], s[22:23], 0, v[0:1]
	s_mov_b32 m0, s24
	s_nop 0
	global_load_lds_dwordx4 v[172:173], off
	v_lshl_add_u64 v[172:173], s[22:23], 0, v[130:131]
	s_add_i32 m0, s24, 0x2000
	s_nop 0
	global_load_lds_dwordx4 v[172:173], off
	v_lshl_add_u64 v[172:173], v[180:181], 0, s[34:35]
	s_mov_b32 m0, s39
	s_nop 0
	global_load_lds_dwordx4 v[172:173], off
	v_lshl_add_u64 v[172:173], v[210:211], 0, s[34:35]
	s_mov_b32 m0, s40
	s_nop 0
	global_load_lds_dwordx4 v[172:173], off
	s_waitcnt vmcnt(8)
	s_waitcnt lgkmcnt(0)
	s_barrier
	s_setprio 1
	s_waitcnt lgkmcnt(0)
	v_mfma_f32_16x16x32_bf16 v[62:65], v[140:143], v[194:197], v[62:65]
	v_mfma_f32_16x16x32_bf16 v[54:57], v[140:143], v[202:205], v[54:57]
	v_mfma_f32_16x16x32_bf16 v[38:41], v[140:143], v[228:231], v[38:41]
	v_mfma_f32_16x16x32_bf16 v[22:25], v[140:143], v[236:239], v[22:25]
	v_mfma_f32_16x16x32_bf16 v[58:61], v[152:155], v[194:197], v[58:61]
	v_mfma_f32_16x16x32_bf16 v[46:49], v[152:155], v[202:205], v[46:49]
	v_mfma_f32_16x16x32_bf16 v[30:33], v[152:155], v[228:231], v[30:33]
	v_mfma_f32_16x16x32_bf16 v[14:17], v[152:155], v[236:239], v[14:17]
	v_mfma_f32_16x16x32_bf16 v[62:65], v[148:151], v[198:201], v[62:65]
	v_mfma_f32_16x16x32_bf16 v[54:57], v[148:151], v[206:209], v[54:57]
	v_mfma_f32_16x16x32_bf16 v[38:41], v[148:151], v[232:235], v[38:41]
	v_mfma_f32_16x16x32_bf16 v[22:25], v[148:151], v[240:243], v[22:25]
	v_mfma_f32_16x16x32_bf16 v[58:61], v[156:159], v[198:201], v[58:61]
	v_mfma_f32_16x16x32_bf16 v[46:49], v[156:159], v[206:209], v[46:49]
	v_mfma_f32_16x16x32_bf16 v[30:33], v[156:159], v[232:235], v[30:33]
	v_mfma_f32_16x16x32_bf16 v[14:17], v[156:159], v[240:243], v[14:17]
	s_setprio 0
	s_setprio 1
	v_mfma_f32_16x16x32_bf16 v[50:53], v[160:163], v[194:197], v[50:53]
	v_mfma_f32_16x16x32_bf16 v[34:37], v[160:163], v[202:205], v[34:37]
	v_mfma_f32_16x16x32_bf16 v[18:21], v[160:163], v[228:231], v[18:21]
	v_mfma_f32_16x16x32_bf16 v[6:9], v[160:163], v[236:239], v[6:9]
	v_mfma_f32_16x16x32_bf16 v[42:45], v[168:171], v[194:197], v[42:45]
	v_mfma_f32_16x16x32_bf16 v[26:29], v[168:171], v[202:205], v[26:29]
	v_mfma_f32_16x16x32_bf16 v[10:13], v[168:171], v[228:231], v[10:13]
	v_mfma_f32_16x16x32_bf16 v[2:5], v[168:171], v[236:239], v[2:5]
	v_mfma_f32_16x16x32_bf16 v[50:53], v[164:167], v[198:201], v[50:53]
	v_mfma_f32_16x16x32_bf16 v[34:37], v[164:167], v[206:209], v[34:37]
	v_mfma_f32_16x16x32_bf16 v[18:21], v[164:167], v[232:235], v[18:21]
	v_mfma_f32_16x16x32_bf16 v[6:9], v[164:167], v[240:243], v[6:9]
	v_mfma_f32_16x16x32_bf16 v[42:45], v[190:193], v[198:201], v[42:45]
	v_mfma_f32_16x16x32_bf16 v[26:29], v[190:193], v[206:209], v[26:29]
	v_mfma_f32_16x16x32_bf16 v[10:13], v[190:193], v[232:235], v[10:13]
	v_mfma_f32_16x16x32_bf16 v[2:5], v[190:193], v[240:243], v[2:5]
	s_setprio 0
	s_barrier
	s_add_i32 s48, s48, 2
	s_add_u32 s18, s18, 0x100
	s_addc_u32 s19, s19, 0
	s_add_u32 s46, s46, 0x100
	s_addc_u32 s47, s47, 0
	s_cmp_gt_u32 s48, 61
	s_cbranch_scc0 .LBB0_139
	s_and_b64 vcc, exec, s[4:5]
	s_cbranch_vccz .LBB0_142
	s_barrier

.LBB0_400:
	s_add_u32 s22, s18, 0xfffc0080
	s_addc_u32 s23, s19, -1
	s_add_i32 s54, 0, 0x10000
	s_cmp_eq_u32 s53, 12
	s_cselect_b32 s25, s9, s23
	s_cselect_b32 s24, s49, s22
	s_cselect_b32 s23, s7, s52
	s_cselect_b32 s22, s50, s51
	s_add_i32 s56, 0, 0x14000
	v_add_u32_e32 v54, s54, v177
	v_add_u32_e32 v142, s56, v177
	ds_read_b128 v[34:37], v54
	ds_read_b128 v[38:41], v54 offset:1024
	ds_read_b128 v[50:53], v54 offset:2048
	ds_read_b128 v[54:57], v54 offset:3072
	ds_read_b128 v[106:109], v142
	ds_read_b128 v[118:121], v142 offset:1024
	ds_read_b128 v[130:133], v142 offset:2048
	ds_read_b128 v[142:145], v142 offset:3072
	v_lshl_add_u64 v[186:187], s[18:19], 0, v[196:197]
	s_add_i32 m0, s40, 0xc000
	ds_read_b128 v[146:149], v229
	ds_read_b128 v[158:161], v229 offset:1024
	ds_read_b128 v[162:165], v229 offset:2048
	ds_read_b128 v[178:181], v229 offset:3072
	ds_read_b128 v[200:203], v229 offset:4096
	ds_read_b128 v[204:207], v229 offset:5120
	ds_read_b128 v[208:211], v229 offset:6144
	ds_read_b128 v[230:233], v229 offset:7168
	global_load_lds_dwordx4 v[186:187], off
	v_lshl_add_u64 v[186:187], s[18:19], 0, v[198:199]
	s_add_i32 m0, s40, 0xe000
	s_nop 0
	global_load_lds_dwordx4 v[186:187], off
	s_waitcnt vmcnt(8)
	s_waitcnt lgkmcnt(0)
	s_barrier
	s_setprio 1
	s_waitcnt lgkmcnt(0)
	v_mfma_f32_16x16x32_bf16 v[170:173], v[34:37], v[146:149], v[170:173]
	v_mfma_f32_16x16x32_bf16 v[138:141], v[34:37], v[162:165], v[138:141]
	v_mfma_f32_16x16x32_bf16 v[114:117], v[34:37], v[200:203], v[114:117]
	v_mfma_f32_16x16x32_bf16 v[94:97], v[34:37], v[208:211], v[94:97]
	v_mfma_f32_16x16x32_bf16 v[166:169], v[50:53], v[146:149], v[166:169]
	v_mfma_f32_16x16x32_bf16 v[134:137], v[50:53], v[162:165], v[134:137]
	v_mfma_f32_16x16x32_bf16 v[110:113], v[50:53], v[200:203], v[110:113]
	v_mfma_f32_16x16x32_bf16 v[90:93], v[50:53], v[208:211], v[90:93]
	v_mfma_f32_16x16x32_bf16 v[170:173], v[38:41], v[158:161], v[170:173]
	v_mfma_f32_16x16x32_bf16 v[138:141], v[38:41], v[178:181], v[138:141]
	v_mfma_f32_16x16x32_bf16 v[114:117], v[38:41], v[204:207], v[114:117]
	v_mfma_f32_16x16x32_bf16 v[94:97], v[38:41], v[230:233], v[94:97]
	v_mfma_f32_16x16x32_bf16 v[166:169], v[54:57], v[158:161], v[166:169]
	v_mfma_f32_16x16x32_bf16 v[134:137], v[54:57], v[178:181], v[134:137]
	v_mfma_f32_16x16x32_bf16 v[110:113], v[54:57], v[204:207], v[110:113]
	v_mfma_f32_16x16x32_bf16 v[90:93], v[54:57], v[230:233], v[90:93]
	s_setprio 0
	s_setprio 1
	v_mfma_f32_16x16x32_bf16 v[154:157], v[106:109], v[146:149], v[154:157]
	v_mfma_f32_16x16x32_bf16 v[126:129], v[106:109], v[162:165], v[126:129]
	v_mfma_f32_16x16x32_bf16 v[122:125], v[130:133], v[162:165], v[122:125]
	v_mfma_f32_16x16x32_bf16 v[102:105], v[106:109], v[200:203], v[102:105]
	v_mfma_f32_16x16x32_bf16 v[98:101], v[130:133], v[200:203], v[98:101]
	v_mfma_f32_16x16x32_bf16 v[86:89], v[106:109], v[208:211], v[86:89]
	v_mfma_f32_16x16x32_bf16 v[82:85], v[130:133], v[208:211], v[82:85]
	v_mfma_f32_16x16x32_bf16 v[154:157], v[118:121], v[158:161], v[154:157]
	v_mfma_f32_16x16x32_bf16 v[146:149], v[130:133], v[146:149], v[150:153]
	v_mfma_f32_16x16x32_bf16 v[126:129], v[118:121], v[178:181], v[126:129]
	v_mfma_f32_16x16x32_bf16 v[122:125], v[142:145], v[178:181], v[122:125]
	v_mfma_f32_16x16x32_bf16 v[102:105], v[118:121], v[204:207], v[102:105]
	v_mfma_f32_16x16x32_bf16 v[98:101], v[142:145], v[204:207], v[98:101]
	v_mfma_f32_16x16x32_bf16 v[86:89], v[118:121], v[230:233], v[86:89]
	v_mfma_f32_16x16x32_bf16 v[82:85], v[142:145], v[230:233], v[82:85]
	v_mfma_f32_16x16x32_bf16 v[146:149], v[142:145], v[158:161], v[146:149]
	s_setprio 0
	s_barrier
	s_add_i32 s54, s54, s39
	v_lshl_add_u64 v[186:187], s[22:23], 0, v[0:1]
	s_mov_b32 m0, s54
	ds_read_b128 v[150:153], v229 offset:16384
	ds_read_b128 v[158:161], v229 offset:17408
	ds_read_b128 v[162:165], v229 offset:18432
	ds_read_b128 v[178:181], v229 offset:19456
	ds_read_b128 v[200:203], v229 offset:20480
	ds_read_b128 v[204:207], v229 offset:21504
	ds_read_b128 v[208:211], v229 offset:22528
	ds_read_b128 v[230:233], v229 offset:23552
	global_load_lds_dwordx4 v[186:187], off
	s_add_i32 m0, s54, 0x2000
	s_add_u32 s54, s22, 0x40000
	v_lshl_add_u64 v[188:189], s[22:23], 0, v[190:191]
	s_addc_u32 s55, s23, 0
	s_add_i32 s56, s56, s39
	global_load_lds_dwordx4 v[188:189], off
	v_lshl_add_u64 v[226:227], s[54:55], 0, v[0:1]
	s_mov_b32 m0, s56
	v_lshl_add_u64 v[234:235], s[24:25], 0, v[192:193]
	global_load_lds_dwordx4 v[226:227], off
	v_lshl_add_u64 v[226:227], s[54:55], 0, v[190:191]
	s_add_i32 m0, s56, 0x2000
	s_nop 0
	global_load_lds_dwordx4 v[226:227], off
	v_lshl_add_u64 v[226:227], s[24:25], 0, v[194:195]
	s_mov_b32 m0, s40
	s_nop 0
	global_load_lds_dwordx4 v[226:227], off
	s_mov_b32 m0, s41
	s_nop 0
	global_load_lds_dwordx4 v[234:235], off
	s_waitcnt vmcnt(8)
	s_waitcnt lgkmcnt(0)
	s_barrier
	s_setprio 1
	s_waitcnt lgkmcnt(0)
	v_mfma_f32_16x16x32_bf16 v[78:81], v[34:37], v[150:153], v[78:81]
	v_mfma_f32_16x16x32_bf16 v[62:65], v[34:37], v[162:165], v[62:65]
	v_mfma_f32_16x16x32_bf16 v[30:33], v[34:37], v[200:203], v[30:33]
	v_mfma_f32_16x16x32_bf16 v[14:17], v[34:37], v[208:211], v[14:17]
	v_mfma_f32_16x16x32_bf16 v[74:77], v[50:53], v[150:153], v[74:77]
	v_mfma_f32_16x16x32_bf16 v[58:61], v[50:53], v[162:165], v[58:61]
	v_mfma_f32_16x16x32_bf16 v[26:29], v[50:53], v[200:203], v[26:29]
	v_mfma_f32_16x16x32_bf16 v[10:13], v[50:53], v[208:211], v[10:13]
	v_mfma_f32_16x16x32_bf16 v[78:81], v[38:41], v[158:161], v[78:81]
	v_mfma_f32_16x16x32_bf16 v[62:65], v[38:41], v[178:181], v[62:65]
	v_mfma_f32_16x16x32_bf16 v[30:33], v[38:41], v[204:207], v[30:33]
	v_mfma_f32_16x16x32_bf16 v[14:17], v[38:41], v[230:233], v[14:17]
	v_mfma_f32_16x16x32_bf16 v[74:77], v[54:57], v[158:161], v[74:77]
	v_mfma_f32_16x16x32_bf16 v[58:61], v[54:57], v[178:181], v[58:61]
	v_mfma_f32_16x16x32_bf16 v[26:29], v[54:57], v[204:207], v[26:29]
	v_mfma_f32_16x16x32_bf16 v[10:13], v[54:57], v[230:233], v[10:13]
	s_setprio 0
	s_setprio 1
	v_mfma_f32_16x16x32_bf16 v[46:49], v[106:109], v[162:165], v[46:49]
	v_mfma_f32_16x16x32_bf16 v[22:25], v[106:109], v[200:203], v[22:25]
	v_mfma_f32_16x16x32_bf16 v[6:9], v[106:109], v[208:211], v[6:9]
	v_mfma_f32_16x16x32_bf16 v[34:37], v[106:109], v[150:153], v[70:73]
	v_mfma_f32_16x16x32_bf16 v[42:45], v[130:133], v[162:165], v[42:45]
	v_mfma_f32_16x16x32_bf16 v[18:21], v[130:133], v[200:203], v[18:21]
	v_mfma_f32_16x16x32_bf16 v[2:5], v[130:133], v[208:211], v[2:5]
	v_mfma_f32_16x16x32_bf16 v[38:41], v[130:133], v[150:153], v[66:69]
	v_mfma_f32_16x16x32_bf16 v[46:49], v[118:121], v[178:181], v[46:49]
	v_mfma_f32_16x16x32_bf16 v[22:25], v[118:121], v[204:207], v[22:25]
	v_mfma_f32_16x16x32_bf16 v[6:9], v[118:121], v[230:233], v[6:9]
	v_mfma_f32_16x16x32_bf16 v[34:37], v[118:121], v[158:161], v[34:37]
	v_mfma_f32_16x16x32_bf16 v[42:45], v[142:145], v[178:181], v[42:45]
	v_mfma_f32_16x16x32_bf16 v[18:21], v[142:145], v[204:207], v[18:21]
	v_mfma_f32_16x16x32_bf16 v[2:5], v[142:145], v[230:233], v[2:5]
	v_mfma_f32_16x16x32_bf16 v[38:41], v[142:145], v[158:161], v[38:41]
	s_setprio 0
	s_barrier
	s_add_i32 s54, 0, 0x18000
	s_add_i32 s55, 0, 0x1c000
	v_add_u32_e32 v70, s54, v177
	v_add_u32_e32 v142, s55, v177
	ds_read_b128 v[50:53], v70
	ds_read_b128 v[54:57], v70 offset:1024
	ds_read_b128 v[66:69], v70 offset:2048
	ds_read_b128 v[70:73], v70 offset:3072
	ds_read_b128 v[106:109], v142
	ds_read_b128 v[118:121], v142 offset:1024
	ds_read_b128 v[130:133], v142 offset:2048
	ds_read_b128 v[142:145], v142 offset:3072
	s_add_u32 s24, s24, 0x40000
	s_addc_u32 s25, s25, 0
	s_mov_b32 m0, s42
	v_lshl_add_u64 v[236:237], s[24:25], 0, v[194:195]
	ds_read_b128 v[150:153], v229 offset:32768
	ds_read_b128 v[158:161], v229 offset:33792
	ds_read_b128 v[162:165], v229 offset:34816
	ds_read_b128 v[178:181], v229 offset:35840
	ds_read_b128 v[200:203], v229 offset:36864
	ds_read_b128 v[204:207], v229 offset:37888
	ds_read_b128 v[208:211], v229 offset:38912
	ds_read_b128 v[230:233], v229 offset:39936
	global_load_lds_dwordx4 v[236:237], off
	v_lshl_add_u64 v[236:237], s[24:25], 0, v[192:193]
	s_mov_b32 m0, s43
	s_nop 0
	global_load_lds_dwordx4 v[236:237], off
	s_waitcnt vmcnt(8)
	s_waitcnt lgkmcnt(0)
	s_barrier
	s_setprio 1
	s_waitcnt lgkmcnt(0)
	v_mfma_f32_16x16x32_bf16 v[170:173], v[50:53], v[150:153], v[170:173]
	v_mfma_f32_16x16x32_bf16 v[138:141], v[50:53], v[162:165], v[138:141]
	v_mfma_f32_16x16x32_bf16 v[114:117], v[50:53], v[200:203], v[114:117]
	v_mfma_f32_16x16x32_bf16 v[94:97], v[50:53], v[208:211], v[94:97]
	v_mfma_f32_16x16x32_bf16 v[166:169], v[66:69], v[150:153], v[166:169]
	v_mfma_f32_16x16x32_bf16 v[134:137], v[66:69], v[162:165], v[134:137]
	v_mfma_f32_16x16x32_bf16 v[110:113], v[66:69], v[200:203], v[110:113]
	v_mfma_f32_16x16x32_bf16 v[90:93], v[66:69], v[208:211], v[90:93]
	v_mfma_f32_16x16x32_bf16 v[170:173], v[54:57], v[158:161], v[170:173]
	v_mfma_f32_16x16x32_bf16 v[138:141], v[54:57], v[178:181], v[138:141]
	v_mfma_f32_16x16x32_bf16 v[114:117], v[54:57], v[204:207], v[114:117]
	v_mfma_f32_16x16x32_bf16 v[94:97], v[54:57], v[230:233], v[94:97]
	v_mfma_f32_16x16x32_bf16 v[166:169], v[70:73], v[158:161], v[166:169]
	v_mfma_f32_16x16x32_bf16 v[134:137], v[70:73], v[178:181], v[134:137]
	v_mfma_f32_16x16x32_bf16 v[110:113], v[70:73], v[204:207], v[110:113]
	v_mfma_f32_16x16x32_bf16 v[90:93], v[70:73], v[230:233], v[90:93]
	s_setprio 0
	s_setprio 1
	v_mfma_f32_16x16x32_bf16 v[154:157], v[106:109], v[150:153], v[154:157]
	v_mfma_f32_16x16x32_bf16 v[126:129], v[106:109], v[162:165], v[126:129]
	v_mfma_f32_16x16x32_bf16 v[102:105], v[106:109], v[200:203], v[102:105]
	v_mfma_f32_16x16x32_bf16 v[86:89], v[106:109], v[208:211], v[86:89]
	v_mfma_f32_16x16x32_bf16 v[146:149], v[130:133], v[150:153], v[146:149]
	v_mfma_f32_16x16x32_bf16 v[122:125], v[130:133], v[162:165], v[122:125]
	v_mfma_f32_16x16x32_bf16 v[98:101], v[130:133], v[200:203], v[98:101]
	v_mfma_f32_16x16x32_bf16 v[82:85], v[130:133], v[208:211], v[82:85]
	v_mfma_f32_16x16x32_bf16 v[154:157], v[118:121], v[158:161], v[154:157]
	v_mfma_f32_16x16x32_bf16 v[126:129], v[118:121], v[178:181], v[126:129]
	v_mfma_f32_16x16x32_bf16 v[102:105], v[118:121], v[204:207], v[102:105]
	v_mfma_f32_16x16x32_bf16 v[86:89], v[118:121], v[230:233], v[86:89]
	v_mfma_f32_16x16x32_bf16 v[150:153], v[142:145], v[158:161], v[146:149]
	v_mfma_f32_16x16x32_bf16 v[122:125], v[142:145], v[178:181], v[122:125]
	v_mfma_f32_16x16x32_bf16 v[98:101], v[142:145], v[204:207], v[98:101]
	v_mfma_f32_16x16x32_bf16 v[82:85], v[142:145], v[230:233], v[82:85]
	s_setprio 0
	s_barrier
	s_add_i32 s24, s54, s39
	v_lshl_add_u64 v[186:187], v[186:187], 0, s[34:35]
	s_mov_b32 m0, s24
	ds_read_b128 v[146:149], v229 offset:49152
	ds_read_b128 v[158:161], v229 offset:50176
	ds_read_b128 v[162:165], v229 offset:51200
	ds_read_b128 v[178:181], v229 offset:52224
	ds_read_b128 v[200:203], v229 offset:53248
	ds_read_b128 v[204:207], v229 offset:54272
	ds_read_b128 v[208:211], v229 offset:55296
	ds_read_b128 v[230:233], v229 offset:56320
	global_load_lds_dwordx4 v[186:187], off
	s_add_i32 m0, s24, 0x2000
	s_add_u32 s22, s22, 0x40080
	v_lshl_add_u64 v[186:187], v[188:189], 0, s[34:35]
	s_addc_u32 s23, s23, 0
	s_add_i32 s24, s55, s39
	global_load_lds_dwordx4 v[186:187], off
	v_lshl_add_u64 v[186:187], s[22:23], 0, v[0:1]
	s_mov_b32 m0, s24
	s_nop 0
	global_load_lds_dwordx4 v[186:187], off
	v_lshl_add_u64 v[186:187], s[22:23], 0, v[190:191]
	s_add_i32 m0, s24, 0x2000
	s_nop 0
	global_load_lds_dwordx4 v[186:187], off
	v_lshl_add_u64 v[186:187], v[226:227], 0, s[34:35]
	s_mov_b32 m0, s44
	s_nop 0
	global_load_lds_dwordx4 v[186:187], off
	v_lshl_add_u64 v[186:187], v[234:235], 0, s[34:35]
	s_mov_b32 m0, s45
	s_nop 0
	global_load_lds_dwordx4 v[186:187], off
	s_waitcnt vmcnt(8)
	s_waitcnt lgkmcnt(0)
	s_barrier
	s_setprio 1
	s_waitcnt lgkmcnt(0)
	v_mfma_f32_16x16x32_bf16 v[78:81], v[50:53], v[146:149], v[78:81]
	v_mfma_f32_16x16x32_bf16 v[62:65], v[50:53], v[162:165], v[62:65]
	v_mfma_f32_16x16x32_bf16 v[30:33], v[50:53], v[200:203], v[30:33]
	v_mfma_f32_16x16x32_bf16 v[14:17], v[50:53], v[208:211], v[14:17]
	v_mfma_f32_16x16x32_bf16 v[74:77], v[66:69], v[146:149], v[74:77]
	v_mfma_f32_16x16x32_bf16 v[58:61], v[66:69], v[162:165], v[58:61]
	v_mfma_f32_16x16x32_bf16 v[26:29], v[66:69], v[200:203], v[26:29]
	v_mfma_f32_16x16x32_bf16 v[10:13], v[66:69], v[208:211], v[10:13]
	v_mfma_f32_16x16x32_bf16 v[78:81], v[54:57], v[158:161], v[78:81]
	v_mfma_f32_16x16x32_bf16 v[62:65], v[54:57], v[178:181], v[62:65]
	v_mfma_f32_16x16x32_bf16 v[30:33], v[54:57], v[204:207], v[30:33]
	v_mfma_f32_16x16x32_bf16 v[14:17], v[54:57], v[230:233], v[14:17]
	v_mfma_f32_16x16x32_bf16 v[74:77], v[70:73], v[158:161], v[74:77]
	v_mfma_f32_16x16x32_bf16 v[58:61], v[70:73], v[178:181], v[58:61]
	v_mfma_f32_16x16x32_bf16 v[26:29], v[70:73], v[204:207], v[26:29]
	v_mfma_f32_16x16x32_bf16 v[10:13], v[70:73], v[230:233], v[10:13]
	s_setprio 0
	s_setprio 1
	v_mfma_f32_16x16x32_bf16 v[34:37], v[106:109], v[146:149], v[34:37]
	v_mfma_f32_16x16x32_bf16 v[70:73], v[118:121], v[158:161], v[34:37]
	v_mfma_f32_16x16x32_bf16 v[34:37], v[130:133], v[146:149], v[38:41]
	v_mfma_f32_16x16x32_bf16 v[66:69], v[142:145], v[158:161], v[34:37]
	v_mfma_f32_16x16x32_bf16 v[34:37], v[106:109], v[162:165], v[46:49]
	v_mfma_f32_16x16x32_bf16 v[46:49], v[118:121], v[178:181], v[34:37]
	v_mfma_f32_16x16x32_bf16 v[34:37], v[130:133], v[162:165], v[42:45]
	v_mfma_f32_16x16x32_bf16 v[22:25], v[106:109], v[200:203], v[22:25]
	v_mfma_f32_16x16x32_bf16 v[18:21], v[130:133], v[200:203], v[18:21]
	v_mfma_f32_16x16x32_bf16 v[6:9], v[106:109], v[208:211], v[6:9]
	v_mfma_f32_16x16x32_bf16 v[2:5], v[130:133], v[208:211], v[2:5]
	v_mfma_f32_16x16x32_bf16 v[42:45], v[142:145], v[178:181], v[34:37]
	v_mfma_f32_16x16x32_bf16 v[22:25], v[118:121], v[204:207], v[22:25]
	v_mfma_f32_16x16x32_bf16 v[18:21], v[142:145], v[204:207], v[18:21]
	v_mfma_f32_16x16x32_bf16 v[6:9], v[118:121], v[230:233], v[6:9]
	v_mfma_f32_16x16x32_bf16 v[2:5], v[142:145], v[230:233], v[2:5]
	s_setprio 0
	s_barrier
	s_add_i32 s53, s53, 2
	s_add_u32 s18, s18, 0x100
	s_addc_u32 s19, s19, 0
	s_add_u32 s51, s51, 0x100
	s_addc_u32 s52, s52, 0
	s_cmp_gt_u32 s53, 13
	s_cbranch_scc0 .LBB0_400
	s_and_b64 vcc, exec, s[4:5]
	s_cbranch_vccz .LBB0_403
	s_barrier

.LBB0_575:
	s_add_u32 s22, s18, 0xfff00080
	s_addc_u32 s23, s19, -1
	s_add_i32 s53, 0, 0x10000
	s_cmp_eq_u32 s52, 60
	s_cselect_b32 s25, s9, s23
	s_cselect_b32 s24, s48, s22
	v_add_u32_e32 v140, s53, v143
	s_cselect_b32 s23, s7, s51
	s_cselect_b32 s22, s49, s50
	s_add_i32 s56, 0, 0x14000
	ds_read_b128 v[146:149], v140
	ds_read_b128 v[150:153], v140 offset:1024
	ds_read_b128 v[154:157], v140 offset:2048
	ds_read_b128 v[158:161], v140 offset:3072
	v_add_u32_e32 v140, s56, v143
	ds_read_b128 v[162:165], v140
	ds_read_b128 v[166:169], v140 offset:1024
	ds_read_b128 v[170:173], v140 offset:2048
	ds_read_b128 v[178:181], v140 offset:3072
	v_lshl_add_u64 v[140:141], s[18:19], 0, v[136:137]
	s_add_i32 m0, s39, 0xc000
	ds_read_b128 v[190:193], v145
	ds_read_b128 v[194:197], v145 offset:1024
	ds_read_b128 v[198:201], v145 offset:2048
	ds_read_b128 v[202:205], v145 offset:3072
	ds_read_b128 v[206:209], v145 offset:4096
	ds_read_b128 v[228:231], v145 offset:5120
	ds_read_b128 v[232:235], v145 offset:6144
	ds_read_b128 v[236:239], v145 offset:7168
	global_load_lds_dwordx4 v[140:141], off
	v_lshl_add_u64 v[140:141], s[18:19], 0, v[138:139]
	s_add_i32 m0, s39, 0xe000
	s_nop 0
	global_load_lds_dwordx4 v[140:141], off
	s_waitcnt vmcnt(8)
	s_waitcnt lgkmcnt(0)
	s_barrier
	s_setprio 1
	s_waitcnt lgkmcnt(0)
	v_mfma_f32_16x16x32_bf16 v[126:129], v[146:149], v[190:193], v[126:129]
	v_mfma_f32_16x16x32_bf16 v[118:121], v[146:149], v[198:201], v[118:121]
	v_mfma_f32_16x16x32_bf16 v[102:105], v[146:149], v[206:209], v[102:105]
	v_mfma_f32_16x16x32_bf16 v[86:89], v[146:149], v[232:235], v[86:89]
	v_mfma_f32_16x16x32_bf16 v[122:125], v[154:157], v[190:193], v[122:125]
	v_mfma_f32_16x16x32_bf16 v[110:113], v[154:157], v[198:201], v[110:113]
	v_mfma_f32_16x16x32_bf16 v[94:97], v[154:157], v[206:209], v[94:97]
	v_mfma_f32_16x16x32_bf16 v[78:81], v[154:157], v[232:235], v[78:81]
	v_mfma_f32_16x16x32_bf16 v[126:129], v[150:153], v[194:197], v[126:129]
	v_mfma_f32_16x16x32_bf16 v[118:121], v[150:153], v[202:205], v[118:121]
	v_mfma_f32_16x16x32_bf16 v[102:105], v[150:153], v[228:231], v[102:105]
	v_mfma_f32_16x16x32_bf16 v[86:89], v[150:153], v[236:239], v[86:89]
	v_mfma_f32_16x16x32_bf16 v[122:125], v[158:161], v[194:197], v[122:125]
	v_mfma_f32_16x16x32_bf16 v[110:113], v[158:161], v[202:205], v[110:113]
	v_mfma_f32_16x16x32_bf16 v[94:97], v[158:161], v[228:231], v[94:97]
	v_mfma_f32_16x16x32_bf16 v[78:81], v[158:161], v[236:239], v[78:81]
	s_setprio 0
	s_setprio 1
	v_mfma_f32_16x16x32_bf16 v[114:117], v[162:165], v[190:193], v[114:117]
	v_mfma_f32_16x16x32_bf16 v[98:101], v[162:165], v[198:201], v[98:101]
	v_mfma_f32_16x16x32_bf16 v[82:85], v[162:165], v[206:209], v[82:85]
	v_mfma_f32_16x16x32_bf16 v[70:73], v[162:165], v[232:235], v[70:73]
	v_mfma_f32_16x16x32_bf16 v[106:109], v[170:173], v[190:193], v[106:109]
	v_mfma_f32_16x16x32_bf16 v[90:93], v[170:173], v[198:201], v[90:93]
	v_mfma_f32_16x16x32_bf16 v[74:77], v[170:173], v[206:209], v[74:77]
	v_mfma_f32_16x16x32_bf16 v[66:69], v[170:173], v[232:235], v[66:69]
	v_mfma_f32_16x16x32_bf16 v[114:117], v[166:169], v[194:197], v[114:117]
	v_mfma_f32_16x16x32_bf16 v[98:101], v[166:169], v[202:205], v[98:101]
	v_mfma_f32_16x16x32_bf16 v[82:85], v[166:169], v[228:231], v[82:85]
	v_mfma_f32_16x16x32_bf16 v[70:73], v[166:169], v[236:239], v[70:73]
	v_mfma_f32_16x16x32_bf16 v[106:109], v[178:181], v[194:197], v[106:109]
	v_mfma_f32_16x16x32_bf16 v[90:93], v[178:181], v[202:205], v[90:93]
	v_mfma_f32_16x16x32_bf16 v[74:77], v[178:181], v[228:231], v[74:77]
	v_mfma_f32_16x16x32_bf16 v[66:69], v[178:181], v[236:239], v[66:69]
	s_setprio 0
	s_barrier
	s_add_i32 s53, s53, s38
	v_lshl_add_u64 v[140:141], s[22:23], 0, v[0:1]
	s_mov_b32 m0, s53
	ds_read_b128 v[190:193], v145 offset:16384
	ds_read_b128 v[194:197], v145 offset:17408
	ds_read_b128 v[198:201], v145 offset:18432
	ds_read_b128 v[202:205], v145 offset:19456
	ds_read_b128 v[206:209], v145 offset:20480
	ds_read_b128 v[228:231], v145 offset:21504
	ds_read_b128 v[232:235], v145 offset:22528
	ds_read_b128 v[236:239], v145 offset:23552
	global_load_lds_dwordx4 v[140:141], off
	s_add_i32 m0, s53, 0x2000
	s_add_u32 s54, s22, 0x100000
	v_lshl_add_u64 v[186:187], s[22:23], 0, v[130:131]
	s_addc_u32 s55, s23, 0
	s_add_i32 s53, s56, s38
	global_load_lds_dwordx4 v[186:187], off
	v_lshl_add_u64 v[188:189], s[54:55], 0, v[0:1]
	s_mov_b32 m0, s53
	v_lshl_add_u64 v[210:211], s[24:25], 0, v[132:133]
	global_load_lds_dwordx4 v[188:189], off
	v_lshl_add_u64 v[188:189], s[54:55], 0, v[130:131]
	s_add_i32 m0, s53, 0x2000
	s_nop 0
	global_load_lds_dwordx4 v[188:189], off
	v_lshl_add_u64 v[188:189], s[24:25], 0, v[134:135]
	s_mov_b32 m0, s39
	s_nop 0
	global_load_lds_dwordx4 v[188:189], off
	s_mov_b32 m0, s40
	s_nop 0
	global_load_lds_dwordx4 v[210:211], off
	s_waitcnt vmcnt(8)
	s_waitcnt lgkmcnt(0)
	s_barrier
	s_setprio 1
	s_waitcnt lgkmcnt(0)
	v_mfma_f32_16x16x32_bf16 v[62:65], v[146:149], v[190:193], v[62:65]
	v_mfma_f32_16x16x32_bf16 v[54:57], v[146:149], v[198:201], v[54:57]
	v_mfma_f32_16x16x32_bf16 v[38:41], v[146:149], v[206:209], v[38:41]
	v_mfma_f32_16x16x32_bf16 v[22:25], v[146:149], v[232:235], v[22:25]
	v_mfma_f32_16x16x32_bf16 v[58:61], v[154:157], v[190:193], v[58:61]
	v_mfma_f32_16x16x32_bf16 v[46:49], v[154:157], v[198:201], v[46:49]
	v_mfma_f32_16x16x32_bf16 v[30:33], v[154:157], v[206:209], v[30:33]
	v_mfma_f32_16x16x32_bf16 v[14:17], v[154:157], v[232:235], v[14:17]
	v_mfma_f32_16x16x32_bf16 v[62:65], v[150:153], v[194:197], v[62:65]
	v_mfma_f32_16x16x32_bf16 v[54:57], v[150:153], v[202:205], v[54:57]
	v_mfma_f32_16x16x32_bf16 v[38:41], v[150:153], v[228:231], v[38:41]
	v_mfma_f32_16x16x32_bf16 v[22:25], v[150:153], v[236:239], v[22:25]
	v_mfma_f32_16x16x32_bf16 v[58:61], v[158:161], v[194:197], v[58:61]
	v_mfma_f32_16x16x32_bf16 v[46:49], v[158:161], v[202:205], v[46:49]
	v_mfma_f32_16x16x32_bf16 v[30:33], v[158:161], v[228:231], v[30:33]
	v_mfma_f32_16x16x32_bf16 v[14:17], v[158:161], v[236:239], v[14:17]
	s_setprio 0
	s_setprio 1
	v_mfma_f32_16x16x32_bf16 v[50:53], v[162:165], v[190:193], v[50:53]
	v_mfma_f32_16x16x32_bf16 v[34:37], v[162:165], v[198:201], v[34:37]
	v_mfma_f32_16x16x32_bf16 v[18:21], v[162:165], v[206:209], v[18:21]
	v_mfma_f32_16x16x32_bf16 v[6:9], v[162:165], v[232:235], v[6:9]
	v_mfma_f32_16x16x32_bf16 v[42:45], v[170:173], v[190:193], v[42:45]
	v_mfma_f32_16x16x32_bf16 v[26:29], v[170:173], v[198:201], v[26:29]
	v_mfma_f32_16x16x32_bf16 v[10:13], v[170:173], v[206:209], v[10:13]
	v_mfma_f32_16x16x32_bf16 v[2:5], v[170:173], v[232:235], v[2:5]
	v_mfma_f32_16x16x32_bf16 v[50:53], v[166:169], v[194:197], v[50:53]
	v_mfma_f32_16x16x32_bf16 v[34:37], v[166:169], v[202:205], v[34:37]
	v_mfma_f32_16x16x32_bf16 v[18:21], v[166:169], v[228:231], v[18:21]
	v_mfma_f32_16x16x32_bf16 v[6:9], v[166:169], v[236:239], v[6:9]
	v_mfma_f32_16x16x32_bf16 v[42:45], v[178:181], v[194:197], v[42:45]
	v_mfma_f32_16x16x32_bf16 v[26:29], v[178:181], v[202:205], v[26:29]
	v_mfma_f32_16x16x32_bf16 v[10:13], v[178:181], v[228:231], v[10:13]
	v_mfma_f32_16x16x32_bf16 v[2:5], v[178:181], v[236:239], v[2:5]
	s_setprio 0
	s_barrier
	s_add_i32 s53, 0, 0x18000
	s_add_i32 s54, 0, 0x1c000
	v_add_u32_e32 v158, s53, v143
	v_add_u32_e32 v175, s54, v143
	ds_read_b128 v[146:149], v158
	ds_read_b128 v[150:153], v158 offset:1024
	ds_read_b128 v[154:157], v158 offset:2048
	ds_read_b128 v[158:161], v158 offset:3072
	ds_read_b128 v[162:165], v175
	ds_read_b128 v[166:169], v175 offset:1024
	ds_read_b128 v[170:173], v175 offset:2048
	ds_read_b128 v[178:181], v175 offset:3072
	s_add_u32 s24, s24, 0x100000
	s_addc_u32 s25, s25, 0
	s_mov_b32 m0, s41
	v_lshl_add_u64 v[226:227], s[24:25], 0, v[134:135]
	ds_read_b128 v[190:193], v145 offset:32768
	ds_read_b128 v[194:197], v145 offset:33792
	ds_read_b128 v[198:201], v145 offset:34816
	ds_read_b128 v[202:205], v145 offset:35840
	ds_read_b128 v[206:209], v145 offset:36864
	ds_read_b128 v[228:231], v145 offset:37888
	ds_read_b128 v[232:235], v145 offset:38912
	ds_read_b128 v[236:239], v145 offset:39936
	global_load_lds_dwordx4 v[226:227], off
	v_lshl_add_u64 v[226:227], s[24:25], 0, v[132:133]
	s_mov_b32 m0, s42
	s_nop 0
	global_load_lds_dwordx4 v[226:227], off
	s_waitcnt vmcnt(8)
	s_waitcnt lgkmcnt(0)
	s_barrier
	s_setprio 1
	s_waitcnt lgkmcnt(0)
	v_mfma_f32_16x16x32_bf16 v[126:129], v[146:149], v[190:193], v[126:129]
	v_mfma_f32_16x16x32_bf16 v[118:121], v[146:149], v[198:201], v[118:121]
	v_mfma_f32_16x16x32_bf16 v[102:105], v[146:149], v[206:209], v[102:105]
	v_mfma_f32_16x16x32_bf16 v[86:89], v[146:149], v[232:235], v[86:89]
	v_mfma_f32_16x16x32_bf16 v[122:125], v[154:157], v[190:193], v[122:125]
	v_mfma_f32_16x16x32_bf16 v[110:113], v[154:157], v[198:201], v[110:113]
	v_mfma_f32_16x16x32_bf16 v[94:97], v[154:157], v[206:209], v[94:97]
	v_mfma_f32_16x16x32_bf16 v[78:81], v[154:157], v[232:235], v[78:81]
	v_mfma_f32_16x16x32_bf16 v[126:129], v[150:153], v[194:197], v[126:129]
	v_mfma_f32_16x16x32_bf16 v[118:121], v[150:153], v[202:205], v[118:121]
	v_mfma_f32_16x16x32_bf16 v[102:105], v[150:153], v[228:231], v[102:105]
	v_mfma_f32_16x16x32_bf16 v[86:89], v[150:153], v[236:239], v[86:89]
	v_mfma_f32_16x16x32_bf16 v[122:125], v[158:161], v[194:197], v[122:125]
	v_mfma_f32_16x16x32_bf16 v[110:113], v[158:161], v[202:205], v[110:113]
	v_mfma_f32_16x16x32_bf16 v[94:97], v[158:161], v[228:231], v[94:97]
	v_mfma_f32_16x16x32_bf16 v[78:81], v[158:161], v[236:239], v[78:81]
	s_setprio 0
	s_setprio 1
	v_mfma_f32_16x16x32_bf16 v[114:117], v[162:165], v[190:193], v[114:117]
	v_mfma_f32_16x16x32_bf16 v[98:101], v[162:165], v[198:201], v[98:101]
	v_mfma_f32_16x16x32_bf16 v[82:85], v[162:165], v[206:209], v[82:85]
	v_mfma_f32_16x16x32_bf16 v[70:73], v[162:165], v[232:235], v[70:73]
	v_mfma_f32_16x16x32_bf16 v[106:109], v[170:173], v[190:193], v[106:109]
	v_mfma_f32_16x16x32_bf16 v[90:93], v[170:173], v[198:201], v[90:93]
	v_mfma_f32_16x16x32_bf16 v[74:77], v[170:173], v[206:209], v[74:77]
	v_mfma_f32_16x16x32_bf16 v[66:69], v[170:173], v[232:235], v[66:69]
	v_mfma_f32_16x16x32_bf16 v[114:117], v[166:169], v[194:197], v[114:117]
	v_mfma_f32_16x16x32_bf16 v[98:101], v[166:169], v[202:205], v[98:101]
	v_mfma_f32_16x16x32_bf16 v[82:85], v[166:169], v[228:231], v[82:85]
	v_mfma_f32_16x16x32_bf16 v[70:73], v[166:169], v[236:239], v[70:73]
	v_mfma_f32_16x16x32_bf16 v[106:109], v[178:181], v[194:197], v[106:109]
	v_mfma_f32_16x16x32_bf16 v[90:93], v[178:181], v[202:205], v[90:93]
	v_mfma_f32_16x16x32_bf16 v[74:77], v[178:181], v[228:231], v[74:77]
	v_mfma_f32_16x16x32_bf16 v[66:69], v[178:181], v[236:239], v[66:69]
	s_setprio 0
	s_barrier
	s_add_i32 s24, s53, s38
	v_lshl_add_u64 v[140:141], v[140:141], 0, s[34:35]
	s_mov_b32 m0, s24
	ds_read_b128 v[190:193], v145 offset:49152
	ds_read_b128 v[194:197], v145 offset:50176
	ds_read_b128 v[198:201], v145 offset:51200
	ds_read_b128 v[202:205], v145 offset:52224
	ds_read_b128 v[206:209], v145 offset:53248
	ds_read_b128 v[228:231], v145 offset:54272
	ds_read_b128 v[232:235], v145 offset:55296
	ds_read_b128 v[236:239], v145 offset:56320
	global_load_lds_dwordx4 v[140:141], off
	s_add_i32 m0, s24, 0x2000
	s_add_u32 s22, s22, 0x100080
	v_lshl_add_u64 v[140:141], v[186:187], 0, s[34:35]
	s_addc_u32 s23, s23, 0
	s_add_i32 s24, s54, s38
	global_load_lds_dwordx4 v[140:141], off
	v_lshl_add_u64 v[140:141], s[22:23], 0, v[0:1]
	s_mov_b32 m0, s24
	s_nop 0
	global_load_lds_dwordx4 v[140:141], off
	v_lshl_add_u64 v[140:141], s[22:23], 0, v[130:131]
	s_add_i32 m0, s24, 0x2000
	s_nop 0
	global_load_lds_dwordx4 v[140:141], off
	v_lshl_add_u64 v[140:141], v[188:189], 0, s[34:35]
	s_mov_b32 m0, s43
	s_nop 0
	global_load_lds_dwordx4 v[140:141], off
	v_lshl_add_u64 v[140:141], v[210:211], 0, s[34:35]
	s_mov_b32 m0, s44
	s_nop 0
	global_load_lds_dwordx4 v[140:141], off
	s_waitcnt vmcnt(8)
	s_waitcnt lgkmcnt(0)
	s_barrier
	s_setprio 1
	s_waitcnt lgkmcnt(0)
	v_mfma_f32_16x16x32_bf16 v[62:65], v[146:149], v[190:193], v[62:65]
	v_mfma_f32_16x16x32_bf16 v[54:57], v[146:149], v[198:201], v[54:57]
	v_mfma_f32_16x16x32_bf16 v[38:41], v[146:149], v[206:209], v[38:41]
	v_mfma_f32_16x16x32_bf16 v[22:25], v[146:149], v[232:235], v[22:25]
	v_mfma_f32_16x16x32_bf16 v[58:61], v[154:157], v[190:193], v[58:61]
	v_mfma_f32_16x16x32_bf16 v[46:49], v[154:157], v[198:201], v[46:49]
	v_mfma_f32_16x16x32_bf16 v[30:33], v[154:157], v[206:209], v[30:33]
	v_mfma_f32_16x16x32_bf16 v[14:17], v[154:157], v[232:235], v[14:17]
	v_mfma_f32_16x16x32_bf16 v[62:65], v[150:153], v[194:197], v[62:65]
	v_mfma_f32_16x16x32_bf16 v[54:57], v[150:153], v[202:205], v[54:57]
	v_mfma_f32_16x16x32_bf16 v[38:41], v[150:153], v[228:231], v[38:41]
	v_mfma_f32_16x16x32_bf16 v[22:25], v[150:153], v[236:239], v[22:25]
	v_mfma_f32_16x16x32_bf16 v[58:61], v[158:161], v[194:197], v[58:61]
	v_mfma_f32_16x16x32_bf16 v[46:49], v[158:161], v[202:205], v[46:49]
	v_mfma_f32_16x16x32_bf16 v[30:33], v[158:161], v[228:231], v[30:33]
	v_mfma_f32_16x16x32_bf16 v[14:17], v[158:161], v[236:239], v[14:17]
	s_setprio 0
	s_setprio 1
	v_mfma_f32_16x16x32_bf16 v[50:53], v[162:165], v[190:193], v[50:53]
	v_mfma_f32_16x16x32_bf16 v[34:37], v[162:165], v[198:201], v[34:37]
	v_mfma_f32_16x16x32_bf16 v[18:21], v[162:165], v[206:209], v[18:21]
	v_mfma_f32_16x16x32_bf16 v[6:9], v[162:165], v[232:235], v[6:9]
	v_mfma_f32_16x16x32_bf16 v[42:45], v[170:173], v[190:193], v[42:45]
	v_mfma_f32_16x16x32_bf16 v[26:29], v[170:173], v[198:201], v[26:29]
	v_mfma_f32_16x16x32_bf16 v[10:13], v[170:173], v[206:209], v[10:13]
	v_mfma_f32_16x16x32_bf16 v[2:5], v[170:173], v[232:235], v[2:5]
	v_mfma_f32_16x16x32_bf16 v[50:53], v[166:169], v[194:197], v[50:53]
	v_mfma_f32_16x16x32_bf16 v[34:37], v[166:169], v[202:205], v[34:37]
	v_mfma_f32_16x16x32_bf16 v[18:21], v[166:169], v[228:231], v[18:21]
	v_mfma_f32_16x16x32_bf16 v[6:9], v[166:169], v[236:239], v[6:9]
	v_mfma_f32_16x16x32_bf16 v[42:45], v[178:181], v[194:197], v[42:45]
	v_mfma_f32_16x16x32_bf16 v[26:29], v[178:181], v[202:205], v[26:29]
	v_mfma_f32_16x16x32_bf16 v[10:13], v[178:181], v[228:231], v[10:13]
	v_mfma_f32_16x16x32_bf16 v[2:5], v[178:181], v[236:239], v[2:5]
	s_setprio 0
	s_barrier
	s_add_i32 s52, s52, 2
	s_add_u32 s18, s18, 0x100
	s_addc_u32 s19, s19, 0
	s_add_u32 s50, s50, 0x100
	s_addc_u32 s51, s51, 0
	s_cmp_gt_u32 s52, 61
	s_cbranch_scc0 .LBB0_575
	s_and_b64 vcc, exec, s[4:5]
	s_cbranch_vccz .LBB0_578
	s_barrier

.LBB0_721:
	s_add_u32 s18, s16, 0xfff00080
	s_addc_u32 s19, s17, -1
	s_add_i32 s53, 0, 0x10000
	s_cmp_eq_u32 s52, 60
	s_cselect_b32 s23, s7, s19
	s_cselect_b32 s22, s48, s18
	v_add_u32_e32 v140, s53, v143
	s_cselect_b32 s19, s5, s51
	s_cselect_b32 s18, s49, s50
	s_add_i32 s56, 0, 0x14000
	ds_read_b128 v[146:149], v140
	ds_read_b128 v[150:153], v140 offset:1024
	ds_read_b128 v[154:157], v140 offset:2048
	ds_read_b128 v[158:161], v140 offset:3072
	v_add_u32_e32 v140, s56, v143
	ds_read_b128 v[162:165], v140
	ds_read_b128 v[166:169], v140 offset:1024
	ds_read_b128 v[170:173], v140 offset:2048
	ds_read_b128 v[178:181], v140 offset:3072
	v_lshl_add_u64 v[140:141], s[16:17], 0, v[136:137]
	s_add_i32 m0, s31, 0xc000
	ds_read_b128 v[190:193], v145
	ds_read_b128 v[194:197], v145 offset:1024
	ds_read_b128 v[198:201], v145 offset:2048
	ds_read_b128 v[202:205], v145 offset:3072
	ds_read_b128 v[206:209], v145 offset:4096
	ds_read_b128 v[228:231], v145 offset:5120
	ds_read_b128 v[232:235], v145 offset:6144
	ds_read_b128 v[236:239], v145 offset:7168
	global_load_lds_dwordx4 v[140:141], off
	v_lshl_add_u64 v[140:141], s[16:17], 0, v[138:139]
	s_add_i32 m0, s31, 0xe000
	s_nop 0
	global_load_lds_dwordx4 v[140:141], off
	s_waitcnt vmcnt(8)
	s_waitcnt lgkmcnt(0)
	s_barrier
	s_setprio 1
	s_waitcnt lgkmcnt(0)
	v_mfma_f32_16x16x32_bf16 v[126:129], v[146:149], v[190:193], v[126:129]
	v_mfma_f32_16x16x32_bf16 v[110:113], v[146:149], v[198:201], v[110:113]
	v_mfma_f32_16x16x32_bf16 v[94:97], v[146:149], v[206:209], v[94:97]
	v_mfma_f32_16x16x32_bf16 v[78:81], v[146:149], v[232:235], v[78:81]
	v_mfma_f32_16x16x32_bf16 v[118:121], v[154:157], v[190:193], v[118:121]
	v_mfma_f32_16x16x32_bf16 v[102:105], v[154:157], v[198:201], v[102:105]
	v_mfma_f32_16x16x32_bf16 v[86:89], v[154:157], v[206:209], v[86:89]
	v_mfma_f32_16x16x32_bf16 v[70:73], v[154:157], v[232:235], v[70:73]
	v_mfma_f32_16x16x32_bf16 v[126:129], v[150:153], v[194:197], v[126:129]
	v_mfma_f32_16x16x32_bf16 v[110:113], v[150:153], v[202:205], v[110:113]
	v_mfma_f32_16x16x32_bf16 v[94:97], v[150:153], v[228:231], v[94:97]
	v_mfma_f32_16x16x32_bf16 v[78:81], v[150:153], v[236:239], v[78:81]
	v_mfma_f32_16x16x32_bf16 v[118:121], v[158:161], v[194:197], v[118:121]
	v_mfma_f32_16x16x32_bf16 v[102:105], v[158:161], v[202:205], v[102:105]
	v_mfma_f32_16x16x32_bf16 v[86:89], v[158:161], v[228:231], v[86:89]
	v_mfma_f32_16x16x32_bf16 v[70:73], v[158:161], v[236:239], v[70:73]
	s_setprio 0
	s_setprio 1
	v_mfma_f32_16x16x32_bf16 v[122:125], v[162:165], v[190:193], v[122:125]
	v_mfma_f32_16x16x32_bf16 v[106:109], v[162:165], v[198:201], v[106:109]
	v_mfma_f32_16x16x32_bf16 v[90:93], v[162:165], v[206:209], v[90:93]
	v_mfma_f32_16x16x32_bf16 v[74:77], v[162:165], v[232:235], v[74:77]
	v_mfma_f32_16x16x32_bf16 v[114:117], v[170:173], v[190:193], v[114:117]
	v_mfma_f32_16x16x32_bf16 v[98:101], v[170:173], v[198:201], v[98:101]
	v_mfma_f32_16x16x32_bf16 v[82:85], v[170:173], v[206:209], v[82:85]
	v_mfma_f32_16x16x32_bf16 v[66:69], v[170:173], v[232:235], v[66:69]
	v_mfma_f32_16x16x32_bf16 v[122:125], v[166:169], v[194:197], v[122:125]
	v_mfma_f32_16x16x32_bf16 v[106:109], v[166:169], v[202:205], v[106:109]
	v_mfma_f32_16x16x32_bf16 v[90:93], v[166:169], v[228:231], v[90:93]
	v_mfma_f32_16x16x32_bf16 v[74:77], v[166:169], v[236:239], v[74:77]
	v_mfma_f32_16x16x32_bf16 v[114:117], v[178:181], v[194:197], v[114:117]
	v_mfma_f32_16x16x32_bf16 v[98:101], v[178:181], v[202:205], v[98:101]
	v_mfma_f32_16x16x32_bf16 v[82:85], v[178:181], v[228:231], v[82:85]
	v_mfma_f32_16x16x32_bf16 v[66:69], v[178:181], v[236:239], v[66:69]
	s_setprio 0
	s_barrier
	s_add_i32 s53, s53, s26
	v_lshl_add_u64 v[140:141], s[18:19], 0, v[0:1]
	s_mov_b32 m0, s53
	ds_read_b128 v[190:193], v145 offset:16384
	ds_read_b128 v[194:197], v145 offset:17408
	ds_read_b128 v[198:201], v145 offset:18432
	ds_read_b128 v[202:205], v145 offset:19456
	ds_read_b128 v[206:209], v145 offset:20480
	ds_read_b128 v[228:231], v145 offset:21504
	ds_read_b128 v[232:235], v145 offset:22528
	ds_read_b128 v[236:239], v145 offset:23552
	global_load_lds_dwordx4 v[140:141], off
	s_add_i32 m0, s53, 0x2000
	s_add_u32 s54, s18, 0x100000
	v_lshl_add_u64 v[186:187], s[18:19], 0, v[130:131]
	s_addc_u32 s55, s19, 0
	s_add_i32 s53, s56, s26
	global_load_lds_dwordx4 v[186:187], off
	v_lshl_add_u64 v[188:189], s[54:55], 0, v[0:1]
	s_mov_b32 m0, s53
	v_lshl_add_u64 v[210:211], s[22:23], 0, v[132:133]
	global_load_lds_dwordx4 v[188:189], off
	v_lshl_add_u64 v[188:189], s[54:55], 0, v[130:131]
	s_add_i32 m0, s53, 0x2000
	s_nop 0
	global_load_lds_dwordx4 v[188:189], off
	v_lshl_add_u64 v[188:189], s[22:23], 0, v[134:135]
	s_mov_b32 m0, s31
	s_nop 0
	global_load_lds_dwordx4 v[188:189], off
	s_mov_b32 m0, s40
	s_nop 0
	global_load_lds_dwordx4 v[210:211], off
	s_waitcnt vmcnt(8)
	s_waitcnt lgkmcnt(0)
	s_barrier
	s_setprio 1
	s_waitcnt lgkmcnt(0)
	v_mfma_f32_16x16x32_bf16 v[62:65], v[146:149], v[190:193], v[62:65]
	v_mfma_f32_16x16x32_bf16 v[46:49], v[146:149], v[198:201], v[46:49]
	v_mfma_f32_16x16x32_bf16 v[30:33], v[146:149], v[206:209], v[30:33]
	v_mfma_f32_16x16x32_bf16 v[14:17], v[146:149], v[232:235], v[14:17]
	v_mfma_f32_16x16x32_bf16 v[54:57], v[154:157], v[190:193], v[54:57]
	v_mfma_f32_16x16x32_bf16 v[38:41], v[154:157], v[198:201], v[38:41]
	v_mfma_f32_16x16x32_bf16 v[22:25], v[154:157], v[206:209], v[22:25]
	v_mfma_f32_16x16x32_bf16 v[6:9], v[154:157], v[232:235], v[6:9]
	v_mfma_f32_16x16x32_bf16 v[62:65], v[150:153], v[194:197], v[62:65]
	v_mfma_f32_16x16x32_bf16 v[46:49], v[150:153], v[202:205], v[46:49]
	v_mfma_f32_16x16x32_bf16 v[30:33], v[150:153], v[228:231], v[30:33]
	v_mfma_f32_16x16x32_bf16 v[14:17], v[150:153], v[236:239], v[14:17]
	v_mfma_f32_16x16x32_bf16 v[54:57], v[158:161], v[194:197], v[54:57]
	v_mfma_f32_16x16x32_bf16 v[38:41], v[158:161], v[202:205], v[38:41]
	v_mfma_f32_16x16x32_bf16 v[22:25], v[158:161], v[228:231], v[22:25]
	v_mfma_f32_16x16x32_bf16 v[6:9], v[158:161], v[236:239], v[6:9]
	s_setprio 0
	s_setprio 1
	v_mfma_f32_16x16x32_bf16 v[58:61], v[162:165], v[190:193], v[58:61]
	v_mfma_f32_16x16x32_bf16 v[42:45], v[162:165], v[198:201], v[42:45]
	v_mfma_f32_16x16x32_bf16 v[26:29], v[162:165], v[206:209], v[26:29]
	v_mfma_f32_16x16x32_bf16 v[10:13], v[162:165], v[232:235], v[10:13]
	v_mfma_f32_16x16x32_bf16 v[50:53], v[170:173], v[190:193], v[50:53]
	v_mfma_f32_16x16x32_bf16 v[34:37], v[170:173], v[198:201], v[34:37]
	v_mfma_f32_16x16x32_bf16 v[18:21], v[170:173], v[206:209], v[18:21]
	v_mfma_f32_16x16x32_bf16 v[2:5], v[170:173], v[232:235], v[2:5]
	v_mfma_f32_16x16x32_bf16 v[58:61], v[166:169], v[194:197], v[58:61]
	v_mfma_f32_16x16x32_bf16 v[42:45], v[166:169], v[202:205], v[42:45]
	v_mfma_f32_16x16x32_bf16 v[26:29], v[166:169], v[228:231], v[26:29]
	v_mfma_f32_16x16x32_bf16 v[10:13], v[166:169], v[236:239], v[10:13]
	v_mfma_f32_16x16x32_bf16 v[50:53], v[178:181], v[194:197], v[50:53]
	v_mfma_f32_16x16x32_bf16 v[34:37], v[178:181], v[202:205], v[34:37]
	v_mfma_f32_16x16x32_bf16 v[18:21], v[178:181], v[228:231], v[18:21]
	v_mfma_f32_16x16x32_bf16 v[2:5], v[178:181], v[236:239], v[2:5]
	s_setprio 0
	s_barrier
	s_add_i32 s53, 0, 0x18000
	s_add_i32 s54, 0, 0x1c000
	v_add_u32_e32 v158, s53, v143
	v_add_u32_e32 v175, s54, v143
	ds_read_b128 v[146:149], v158
	ds_read_b128 v[150:153], v158 offset:1024
	ds_read_b128 v[154:157], v158 offset:2048
	ds_read_b128 v[158:161], v158 offset:3072
	ds_read_b128 v[162:165], v175
	ds_read_b128 v[166:169], v175 offset:1024
	ds_read_b128 v[170:173], v175 offset:2048
	ds_read_b128 v[178:181], v175 offset:3072
	s_add_u32 s22, s22, 0x100000
	s_addc_u32 s23, s23, 0
	s_mov_b32 m0, s41
	v_lshl_add_u64 v[226:227], s[22:23], 0, v[134:135]
	ds_read_b128 v[190:193], v145 offset:32768
	ds_read_b128 v[194:197], v145 offset:33792
	ds_read_b128 v[198:201], v145 offset:34816
	ds_read_b128 v[202:205], v145 offset:35840
	ds_read_b128 v[206:209], v145 offset:36864
	ds_read_b128 v[228:231], v145 offset:37888
	ds_read_b128 v[232:235], v145 offset:38912
	ds_read_b128 v[236:239], v145 offset:39936
	global_load_lds_dwordx4 v[226:227], off
	v_lshl_add_u64 v[226:227], s[22:23], 0, v[132:133]
	s_mov_b32 m0, s42
	s_nop 0
	global_load_lds_dwordx4 v[226:227], off
	s_waitcnt vmcnt(8)
	s_waitcnt lgkmcnt(0)
	s_barrier
	s_setprio 1
	s_waitcnt lgkmcnt(0)
	v_mfma_f32_16x16x32_bf16 v[126:129], v[146:149], v[190:193], v[126:129]
	v_mfma_f32_16x16x32_bf16 v[110:113], v[146:149], v[198:201], v[110:113]
	v_mfma_f32_16x16x32_bf16 v[94:97], v[146:149], v[206:209], v[94:97]
	v_mfma_f32_16x16x32_bf16 v[78:81], v[146:149], v[232:235], v[78:81]
	v_mfma_f32_16x16x32_bf16 v[118:121], v[154:157], v[190:193], v[118:121]
	v_mfma_f32_16x16x32_bf16 v[102:105], v[154:157], v[198:201], v[102:105]
	v_mfma_f32_16x16x32_bf16 v[86:89], v[154:157], v[206:209], v[86:89]
	v_mfma_f32_16x16x32_bf16 v[70:73], v[154:157], v[232:235], v[70:73]
	v_mfma_f32_16x16x32_bf16 v[126:129], v[150:153], v[194:197], v[126:129]
	v_mfma_f32_16x16x32_bf16 v[110:113], v[150:153], v[202:205], v[110:113]
	v_mfma_f32_16x16x32_bf16 v[94:97], v[150:153], v[228:231], v[94:97]
	v_mfma_f32_16x16x32_bf16 v[78:81], v[150:153], v[236:239], v[78:81]
	v_mfma_f32_16x16x32_bf16 v[118:121], v[158:161], v[194:197], v[118:121]
	v_mfma_f32_16x16x32_bf16 v[102:105], v[158:161], v[202:205], v[102:105]
	v_mfma_f32_16x16x32_bf16 v[86:89], v[158:161], v[228:231], v[86:89]
	v_mfma_f32_16x16x32_bf16 v[70:73], v[158:161], v[236:239], v[70:73]
	s_setprio 0
	s_setprio 1
	v_mfma_f32_16x16x32_bf16 v[122:125], v[162:165], v[190:193], v[122:125]
	v_mfma_f32_16x16x32_bf16 v[106:109], v[162:165], v[198:201], v[106:109]
	v_mfma_f32_16x16x32_bf16 v[90:93], v[162:165], v[206:209], v[90:93]
	v_mfma_f32_16x16x32_bf16 v[74:77], v[162:165], v[232:235], v[74:77]
	v_mfma_f32_16x16x32_bf16 v[114:117], v[170:173], v[190:193], v[114:117]
	v_mfma_f32_16x16x32_bf16 v[98:101], v[170:173], v[198:201], v[98:101]
	v_mfma_f32_16x16x32_bf16 v[82:85], v[170:173], v[206:209], v[82:85]
	v_mfma_f32_16x16x32_bf16 v[66:69], v[170:173], v[232:235], v[66:69]
	v_mfma_f32_16x16x32_bf16 v[122:125], v[166:169], v[194:197], v[122:125]
	v_mfma_f32_16x16x32_bf16 v[106:109], v[166:169], v[202:205], v[106:109]
	v_mfma_f32_16x16x32_bf16 v[90:93], v[166:169], v[228:231], v[90:93]
	v_mfma_f32_16x16x32_bf16 v[74:77], v[166:169], v[236:239], v[74:77]
	v_mfma_f32_16x16x32_bf16 v[114:117], v[178:181], v[194:197], v[114:117]
	v_mfma_f32_16x16x32_bf16 v[98:101], v[178:181], v[202:205], v[98:101]
	v_mfma_f32_16x16x32_bf16 v[82:85], v[178:181], v[228:231], v[82:85]
	v_mfma_f32_16x16x32_bf16 v[66:69], v[178:181], v[236:239], v[66:69]
	s_setprio 0
	s_barrier
	s_add_i32 s22, s53, s26
	v_lshl_add_u64 v[140:141], v[140:141], 0, s[34:35]
	s_mov_b32 m0, s22
	ds_read_b128 v[190:193], v145 offset:49152
	ds_read_b128 v[194:197], v145 offset:50176
	ds_read_b128 v[198:201], v145 offset:51200
	ds_read_b128 v[202:205], v145 offset:52224
	ds_read_b128 v[206:209], v145 offset:53248
	ds_read_b128 v[228:231], v145 offset:54272
	ds_read_b128 v[232:235], v145 offset:55296
	ds_read_b128 v[236:239], v145 offset:56320
	global_load_lds_dwordx4 v[140:141], off
	s_add_i32 m0, s22, 0x2000
	s_add_u32 s18, s18, 0x100080
	v_lshl_add_u64 v[140:141], v[186:187], 0, s[34:35]
	s_addc_u32 s19, s19, 0
	s_add_i32 s22, s54, s26
	global_load_lds_dwordx4 v[140:141], off
	v_lshl_add_u64 v[140:141], s[18:19], 0, v[0:1]
	s_mov_b32 m0, s22
	s_nop 0
	global_load_lds_dwordx4 v[140:141], off
	v_lshl_add_u64 v[140:141], s[18:19], 0, v[130:131]
	s_add_i32 m0, s22, 0x2000
	s_nop 0
	global_load_lds_dwordx4 v[140:141], off
	v_lshl_add_u64 v[140:141], v[188:189], 0, s[34:35]
	s_mov_b32 m0, s43
	s_nop 0
	global_load_lds_dwordx4 v[140:141], off
	v_lshl_add_u64 v[140:141], v[210:211], 0, s[34:35]
	s_mov_b32 m0, s44
	s_nop 0
	global_load_lds_dwordx4 v[140:141], off
	s_waitcnt vmcnt(8)
	s_waitcnt lgkmcnt(0)
	s_barrier
	s_setprio 1
	s_waitcnt lgkmcnt(0)
	v_mfma_f32_16x16x32_bf16 v[62:65], v[146:149], v[190:193], v[62:65]
	v_mfma_f32_16x16x32_bf16 v[46:49], v[146:149], v[198:201], v[46:49]
	v_mfma_f32_16x16x32_bf16 v[30:33], v[146:149], v[206:209], v[30:33]
	v_mfma_f32_16x16x32_bf16 v[14:17], v[146:149], v[232:235], v[14:17]
	v_mfma_f32_16x16x32_bf16 v[54:57], v[154:157], v[190:193], v[54:57]
	v_mfma_f32_16x16x32_bf16 v[38:41], v[154:157], v[198:201], v[38:41]
	v_mfma_f32_16x16x32_bf16 v[22:25], v[154:157], v[206:209], v[22:25]
	v_mfma_f32_16x16x32_bf16 v[6:9], v[154:157], v[232:235], v[6:9]
	v_mfma_f32_16x16x32_bf16 v[62:65], v[150:153], v[194:197], v[62:65]
	v_mfma_f32_16x16x32_bf16 v[46:49], v[150:153], v[202:205], v[46:49]
	v_mfma_f32_16x16x32_bf16 v[30:33], v[150:153], v[228:231], v[30:33]
	v_mfma_f32_16x16x32_bf16 v[14:17], v[150:153], v[236:239], v[14:17]
	v_mfma_f32_16x16x32_bf16 v[54:57], v[158:161], v[194:197], v[54:57]
	v_mfma_f32_16x16x32_bf16 v[38:41], v[158:161], v[202:205], v[38:41]
	v_mfma_f32_16x16x32_bf16 v[22:25], v[158:161], v[228:231], v[22:25]
	v_mfma_f32_16x16x32_bf16 v[6:9], v[158:161], v[236:239], v[6:9]
	s_setprio 0
	s_setprio 1
	v_mfma_f32_16x16x32_bf16 v[58:61], v[162:165], v[190:193], v[58:61]
	v_mfma_f32_16x16x32_bf16 v[42:45], v[162:165], v[198:201], v[42:45]
	v_mfma_f32_16x16x32_bf16 v[26:29], v[162:165], v[206:209], v[26:29]
	v_mfma_f32_16x16x32_bf16 v[10:13], v[162:165], v[232:235], v[10:13]
	v_mfma_f32_16x16x32_bf16 v[50:53], v[170:173], v[190:193], v[50:53]
	v_mfma_f32_16x16x32_bf16 v[34:37], v[170:173], v[198:201], v[34:37]
	v_mfma_f32_16x16x32_bf16 v[18:21], v[170:173], v[206:209], v[18:21]
	v_mfma_f32_16x16x32_bf16 v[2:5], v[170:173], v[232:235], v[2:5]
	v_mfma_f32_16x16x32_bf16 v[58:61], v[166:169], v[194:197], v[58:61]
	v_mfma_f32_16x16x32_bf16 v[42:45], v[166:169], v[202:205], v[42:45]
	v_mfma_f32_16x16x32_bf16 v[26:29], v[166:169], v[228:231], v[26:29]
	v_mfma_f32_16x16x32_bf16 v[10:13], v[166:169], v[236:239], v[10:13]
	v_mfma_f32_16x16x32_bf16 v[50:53], v[178:181], v[194:197], v[50:53]
	v_mfma_f32_16x16x32_bf16 v[34:37], v[178:181], v[202:205], v[34:37]
	v_mfma_f32_16x16x32_bf16 v[18:21], v[178:181], v[228:231], v[18:21]
	v_mfma_f32_16x16x32_bf16 v[2:5], v[178:181], v[236:239], v[2:5]
	s_setprio 0
	s_barrier
	s_add_i32 s52, s52, 2
	s_add_u32 s16, s16, 0x100
	s_addc_u32 s17, s17, 0
	s_add_u32 s50, s50, 0x100
	s_addc_u32 s51, s51, 0
	s_cmp_gt_u32 s52, 61
	s_cbranch_scc0 .LBB0_721
	s_and_b64 vcc, exec, s[2:3]
	s_cbranch_vccz .LBB0_724
	s_barrier

.LBB0_805:
	s_add_u32 s16, s14, 0x100
	s_addc_u32 s17, s15, 0
	s_add_i32 s49, 0, 0x10000
	s_cmpk_eq_i32 s48, 0xa8
	s_cselect_b32 s23, s5, s17
	s_cselect_b32 s22, s4, s16
	v_add_u32_e32 v140, s49, v143
	s_cselect_b32 s19, s9, s47
	s_cselect_b32 s18, s8, s46
	s_add_i32 s50, 0, 0x14000
	ds_read_b128 v[146:149], v140
	ds_read_b128 v[150:153], v140 offset:1024
	ds_read_b128 v[154:157], v140 offset:2048
	ds_read_b128 v[158:161], v140 offset:3072
	v_add_u32_e32 v140, s50, v143
	ds_read_b128 v[162:165], v140
	ds_read_b128 v[166:169], v140 offset:1024
	ds_read_b128 v[170:173], v140 offset:2048
	ds_read_b128 v[178:181], v140 offset:3072
	v_lshl_add_u64 v[140:141], s[14:15], 0, v[136:137]
	s_add_i32 m0, s31, 0xc000
	ds_read_b128 v[190:193], v145
	ds_read_b128 v[194:197], v145 offset:1024
	ds_read_b128 v[198:201], v145 offset:2048
	ds_read_b128 v[202:205], v145 offset:3072
	ds_read_b128 v[206:209], v145 offset:4096
	ds_read_b128 v[228:231], v145 offset:5120
	ds_read_b128 v[232:235], v145 offset:6144
	ds_read_b128 v[236:239], v145 offset:7168
	global_load_lds_dwordx4 v[140:141], off
	v_lshl_add_u64 v[140:141], s[14:15], 0, v[138:139]
	s_add_i32 m0, s31, 0xe000
	s_nop 0
	global_load_lds_dwordx4 v[140:141], off
	s_waitcnt vmcnt(8)
	s_waitcnt lgkmcnt(0)
	s_barrier
	s_setprio 1
	s_waitcnt lgkmcnt(0)
	v_mfma_f32_16x16x32_bf16 v[126:129], v[146:149], v[190:193], v[126:129]
	v_mfma_f32_16x16x32_bf16 v[118:121], v[146:149], v[198:201], v[118:121]
	v_mfma_f32_16x16x32_bf16 v[102:105], v[146:149], v[206:209], v[102:105]
	v_mfma_f32_16x16x32_bf16 v[86:89], v[146:149], v[232:235], v[86:89]
	v_mfma_f32_16x16x32_bf16 v[122:125], v[154:157], v[190:193], v[122:125]
	v_mfma_f32_16x16x32_bf16 v[110:113], v[154:157], v[198:201], v[110:113]
	v_mfma_f32_16x16x32_bf16 v[94:97], v[154:157], v[206:209], v[94:97]
	v_mfma_f32_16x16x32_bf16 v[78:81], v[154:157], v[232:235], v[78:81]
	v_mfma_f32_16x16x32_bf16 v[126:129], v[150:153], v[194:197], v[126:129]
	v_mfma_f32_16x16x32_bf16 v[118:121], v[150:153], v[202:205], v[118:121]
	v_mfma_f32_16x16x32_bf16 v[102:105], v[150:153], v[228:231], v[102:105]
	v_mfma_f32_16x16x32_bf16 v[86:89], v[150:153], v[236:239], v[86:89]
	v_mfma_f32_16x16x32_bf16 v[122:125], v[158:161], v[194:197], v[122:125]
	v_mfma_f32_16x16x32_bf16 v[110:113], v[158:161], v[202:205], v[110:113]
	v_mfma_f32_16x16x32_bf16 v[94:97], v[158:161], v[228:231], v[94:97]
	v_mfma_f32_16x16x32_bf16 v[78:81], v[158:161], v[236:239], v[78:81]
	s_setprio 0
	s_setprio 1
	v_mfma_f32_16x16x32_bf16 v[114:117], v[162:165], v[190:193], v[114:117]
	v_mfma_f32_16x16x32_bf16 v[98:101], v[162:165], v[198:201], v[98:101]
	v_mfma_f32_16x16x32_bf16 v[82:85], v[162:165], v[206:209], v[82:85]
	v_mfma_f32_16x16x32_bf16 v[70:73], v[162:165], v[232:235], v[70:73]
	v_mfma_f32_16x16x32_bf16 v[106:109], v[170:173], v[190:193], v[106:109]
	v_mfma_f32_16x16x32_bf16 v[90:93], v[170:173], v[198:201], v[90:93]
	v_mfma_f32_16x16x32_bf16 v[74:77], v[170:173], v[206:209], v[74:77]
	v_mfma_f32_16x16x32_bf16 v[66:69], v[170:173], v[232:235], v[66:69]
	v_mfma_f32_16x16x32_bf16 v[114:117], v[166:169], v[194:197], v[114:117]
	v_mfma_f32_16x16x32_bf16 v[98:101], v[166:169], v[202:205], v[98:101]
	v_mfma_f32_16x16x32_bf16 v[82:85], v[166:169], v[228:231], v[82:85]
	v_mfma_f32_16x16x32_bf16 v[70:73], v[166:169], v[236:239], v[70:73]
	v_mfma_f32_16x16x32_bf16 v[106:109], v[178:181], v[194:197], v[106:109]
	v_mfma_f32_16x16x32_bf16 v[90:93], v[178:181], v[202:205], v[90:93]
	v_mfma_f32_16x16x32_bf16 v[74:77], v[178:181], v[228:231], v[74:77]
	v_mfma_f32_16x16x32_bf16 v[66:69], v[178:181], v[236:239], v[66:69]
	s_setprio 0
	s_barrier
	s_add_i32 s14, s49, s26
	v_lshl_add_u64 v[140:141], s[18:19], 0, v[0:1]
	s_mov_b32 m0, s14
	ds_read_b128 v[190:193], v145 offset:16384
	ds_read_b128 v[194:197], v145 offset:17408
	ds_read_b128 v[198:201], v145 offset:18432
	ds_read_b128 v[202:205], v145 offset:19456
	ds_read_b128 v[206:209], v145 offset:20480
	ds_read_b128 v[228:231], v145 offset:21504
	ds_read_b128 v[232:235], v145 offset:22528
	ds_read_b128 v[236:239], v145 offset:23552
	global_load_lds_dwordx4 v[140:141], off
	s_add_i32 m0, s14, 0x2000
	s_add_u32 s14, s18, 0x2b0000
	v_lshl_add_u64 v[186:187], s[18:19], 0, v[130:131]
	s_addc_u32 s15, s19, 0
	s_add_i32 s49, s50, s26
	global_load_lds_dwordx4 v[186:187], off
	v_lshl_add_u64 v[188:189], s[14:15], 0, v[0:1]
	s_mov_b32 m0, s49
	v_lshl_add_u64 v[210:211], s[22:23], 0, v[132:133]
	global_load_lds_dwordx4 v[188:189], off
	v_lshl_add_u64 v[188:189], s[14:15], 0, v[130:131]
	s_add_i32 m0, s49, 0x2000
	s_nop 0
	global_load_lds_dwordx4 v[188:189], off
	v_lshl_add_u64 v[188:189], s[22:23], 0, v[134:135]
	s_mov_b32 m0, s31
	s_nop 0
	global_load_lds_dwordx4 v[188:189], off
	s_mov_b32 m0, s36
	s_nop 0
	global_load_lds_dwordx4 v[210:211], off
	s_waitcnt vmcnt(8)
	s_waitcnt lgkmcnt(0)
	s_barrier
	s_setprio 1
	s_waitcnt lgkmcnt(0)
	v_mfma_f32_16x16x32_bf16 v[62:65], v[146:149], v[190:193], v[62:65]
	v_mfma_f32_16x16x32_bf16 v[54:57], v[146:149], v[198:201], v[54:57]
	v_mfma_f32_16x16x32_bf16 v[38:41], v[146:149], v[206:209], v[38:41]
	v_mfma_f32_16x16x32_bf16 v[22:25], v[146:149], v[232:235], v[22:25]
	v_mfma_f32_16x16x32_bf16 v[58:61], v[154:157], v[190:193], v[58:61]
	v_mfma_f32_16x16x32_bf16 v[46:49], v[154:157], v[198:201], v[46:49]
	v_mfma_f32_16x16x32_bf16 v[30:33], v[154:157], v[206:209], v[30:33]
	v_mfma_f32_16x16x32_bf16 v[14:17], v[154:157], v[232:235], v[14:17]
	v_mfma_f32_16x16x32_bf16 v[62:65], v[150:153], v[194:197], v[62:65]
	v_mfma_f32_16x16x32_bf16 v[54:57], v[150:153], v[202:205], v[54:57]
	v_mfma_f32_16x16x32_bf16 v[38:41], v[150:153], v[228:231], v[38:41]
	v_mfma_f32_16x16x32_bf16 v[22:25], v[150:153], v[236:239], v[22:25]
	v_mfma_f32_16x16x32_bf16 v[58:61], v[158:161], v[194:197], v[58:61]
	v_mfma_f32_16x16x32_bf16 v[46:49], v[158:161], v[202:205], v[46:49]
	v_mfma_f32_16x16x32_bf16 v[30:33], v[158:161], v[228:231], v[30:33]
	v_mfma_f32_16x16x32_bf16 v[14:17], v[158:161], v[236:239], v[14:17]
	s_setprio 0
	s_setprio 1
	v_mfma_f32_16x16x32_bf16 v[50:53], v[162:165], v[190:193], v[50:53]
	v_mfma_f32_16x16x32_bf16 v[34:37], v[162:165], v[198:201], v[34:37]
	v_mfma_f32_16x16x32_bf16 v[18:21], v[162:165], v[206:209], v[18:21]
	v_mfma_f32_16x16x32_bf16 v[6:9], v[162:165], v[232:235], v[6:9]
	v_mfma_f32_16x16x32_bf16 v[42:45], v[170:173], v[190:193], v[42:45]
	v_mfma_f32_16x16x32_bf16 v[26:29], v[170:173], v[198:201], v[26:29]
	v_mfma_f32_16x16x32_bf16 v[10:13], v[170:173], v[206:209], v[10:13]
	v_mfma_f32_16x16x32_bf16 v[2:5], v[170:173], v[232:235], v[2:5]
	v_mfma_f32_16x16x32_bf16 v[50:53], v[166:169], v[194:197], v[50:53]
	v_mfma_f32_16x16x32_bf16 v[34:37], v[166:169], v[202:205], v[34:37]
	v_mfma_f32_16x16x32_bf16 v[18:21], v[166:169], v[228:231], v[18:21]
	v_mfma_f32_16x16x32_bf16 v[6:9], v[166:169], v[236:239], v[6:9]
	v_mfma_f32_16x16x32_bf16 v[42:45], v[178:181], v[194:197], v[42:45]
	v_mfma_f32_16x16x32_bf16 v[26:29], v[178:181], v[202:205], v[26:29]
	v_mfma_f32_16x16x32_bf16 v[10:13], v[178:181], v[228:231], v[10:13]
	v_mfma_f32_16x16x32_bf16 v[2:5], v[178:181], v[236:239], v[2:5]
	s_setprio 0
	s_barrier
	s_add_i32 s49, 0, 0x18000
	s_add_i32 s50, 0, 0x1c000
	v_add_u32_e32 v158, s49, v143
	v_add_u32_e32 v175, s50, v143
	ds_read_b128 v[146:149], v158
	ds_read_b128 v[150:153], v158 offset:1024
	ds_read_b128 v[154:157], v158 offset:2048
	ds_read_b128 v[158:161], v158 offset:3072
	ds_read_b128 v[162:165], v175
	ds_read_b128 v[166:169], v175 offset:1024
	ds_read_b128 v[170:173], v175 offset:2048
	ds_read_b128 v[178:181], v175 offset:3072
	s_add_u32 s14, s22, 0x2b0000
	s_addc_u32 s15, s23, 0
	s_mov_b32 m0, s37
	v_lshl_add_u64 v[226:227], s[14:15], 0, v[134:135]
	ds_read_b128 v[190:193], v145 offset:32768
	ds_read_b128 v[194:197], v145 offset:33792
	ds_read_b128 v[198:201], v145 offset:34816
	ds_read_b128 v[202:205], v145 offset:35840
	ds_read_b128 v[206:209], v145 offset:36864
	ds_read_b128 v[228:231], v145 offset:37888
	ds_read_b128 v[232:235], v145 offset:38912
	ds_read_b128 v[236:239], v145 offset:39936
	global_load_lds_dwordx4 v[226:227], off
	v_lshl_add_u64 v[226:227], s[14:15], 0, v[132:133]
	s_mov_b32 m0, s38
	s_nop 0
	global_load_lds_dwordx4 v[226:227], off
	s_waitcnt vmcnt(8)
	s_waitcnt lgkmcnt(0)
	s_barrier
	s_setprio 1
	s_waitcnt lgkmcnt(0)
	v_mfma_f32_16x16x32_bf16 v[126:129], v[146:149], v[190:193], v[126:129]
	v_mfma_f32_16x16x32_bf16 v[118:121], v[146:149], v[198:201], v[118:121]
	v_mfma_f32_16x16x32_bf16 v[102:105], v[146:149], v[206:209], v[102:105]
	v_mfma_f32_16x16x32_bf16 v[86:89], v[146:149], v[232:235], v[86:89]
	v_mfma_f32_16x16x32_bf16 v[122:125], v[154:157], v[190:193], v[122:125]
	v_mfma_f32_16x16x32_bf16 v[110:113], v[154:157], v[198:201], v[110:113]
	v_mfma_f32_16x16x32_bf16 v[94:97], v[154:157], v[206:209], v[94:97]
	v_mfma_f32_16x16x32_bf16 v[78:81], v[154:157], v[232:235], v[78:81]
	v_mfma_f32_16x16x32_bf16 v[126:129], v[150:153], v[194:197], v[126:129]
	v_mfma_f32_16x16x32_bf16 v[118:121], v[150:153], v[202:205], v[118:121]
	v_mfma_f32_16x16x32_bf16 v[102:105], v[150:153], v[228:231], v[102:105]
	v_mfma_f32_16x16x32_bf16 v[86:89], v[150:153], v[236:239], v[86:89]
	v_mfma_f32_16x16x32_bf16 v[122:125], v[158:161], v[194:197], v[122:125]
	v_mfma_f32_16x16x32_bf16 v[110:113], v[158:161], v[202:205], v[110:113]
	v_mfma_f32_16x16x32_bf16 v[94:97], v[158:161], v[228:231], v[94:97]
	v_mfma_f32_16x16x32_bf16 v[78:81], v[158:161], v[236:239], v[78:81]
	s_setprio 0
	s_setprio 1
	v_mfma_f32_16x16x32_bf16 v[114:117], v[162:165], v[190:193], v[114:117]
	v_mfma_f32_16x16x32_bf16 v[98:101], v[162:165], v[198:201], v[98:101]
	v_mfma_f32_16x16x32_bf16 v[82:85], v[162:165], v[206:209], v[82:85]
	v_mfma_f32_16x16x32_bf16 v[70:73], v[162:165], v[232:235], v[70:73]
	v_mfma_f32_16x16x32_bf16 v[106:109], v[170:173], v[190:193], v[106:109]
	v_mfma_f32_16x16x32_bf16 v[90:93], v[170:173], v[198:201], v[90:93]
	v_mfma_f32_16x16x32_bf16 v[74:77], v[170:173], v[206:209], v[74:77]
	v_mfma_f32_16x16x32_bf16 v[66:69], v[170:173], v[232:235], v[66:69]
	v_mfma_f32_16x16x32_bf16 v[114:117], v[166:169], v[194:197], v[114:117]
	v_mfma_f32_16x16x32_bf16 v[98:101], v[166:169], v[202:205], v[98:101]
	v_mfma_f32_16x16x32_bf16 v[82:85], v[166:169], v[228:231], v[82:85]
	v_mfma_f32_16x16x32_bf16 v[70:73], v[166:169], v[236:239], v[70:73]
	v_mfma_f32_16x16x32_bf16 v[106:109], v[178:181], v[194:197], v[106:109]
	v_mfma_f32_16x16x32_bf16 v[90:93], v[178:181], v[202:205], v[90:93]
	v_mfma_f32_16x16x32_bf16 v[74:77], v[178:181], v[228:231], v[74:77]
	v_mfma_f32_16x16x32_bf16 v[66:69], v[178:181], v[236:239], v[66:69]
	s_setprio 0
	s_barrier
	s_add_i32 s14, s49, s26
	v_lshl_add_u64 v[140:141], v[140:141], 0, s[34:35]
	s_mov_b32 m0, s14
	ds_read_b128 v[190:193], v145 offset:49152
	ds_read_b128 v[194:197], v145 offset:50176
	ds_read_b128 v[198:201], v145 offset:51200
	ds_read_b128 v[202:205], v145 offset:52224
	ds_read_b128 v[206:209], v145 offset:53248
	ds_read_b128 v[228:231], v145 offset:54272
	ds_read_b128 v[232:235], v145 offset:55296
	ds_read_b128 v[236:239], v145 offset:56320
	global_load_lds_dwordx4 v[140:141], off
	s_add_i32 m0, s14, 0x2000
	s_add_u32 s14, s18, 0x2b0080
	v_lshl_add_u64 v[140:141], v[186:187], 0, s[34:35]
	s_addc_u32 s15, s19, 0
	s_add_i32 s18, s50, s26
	global_load_lds_dwordx4 v[140:141], off
	v_lshl_add_u64 v[140:141], s[14:15], 0, v[0:1]
	s_mov_b32 m0, s18
	s_nop 0
	global_load_lds_dwordx4 v[140:141], off
	v_lshl_add_u64 v[140:141], s[14:15], 0, v[130:131]
	s_add_i32 m0, s18, 0x2000
	s_nop 0
	global_load_lds_dwordx4 v[140:141], off
	v_lshl_add_u64 v[140:141], v[188:189], 0, s[34:35]
	s_mov_b32 m0, s39
	s_nop 0
	global_load_lds_dwordx4 v[140:141], off
	v_lshl_add_u64 v[140:141], v[210:211], 0, s[34:35]
	s_mov_b32 m0, s40
	s_nop 0
	global_load_lds_dwordx4 v[140:141], off
	s_waitcnt vmcnt(8)
	s_waitcnt lgkmcnt(0)
	s_barrier
	s_setprio 1
	s_waitcnt lgkmcnt(0)
	v_mfma_f32_16x16x32_bf16 v[62:65], v[146:149], v[190:193], v[62:65]
	v_mfma_f32_16x16x32_bf16 v[54:57], v[146:149], v[198:201], v[54:57]
	v_mfma_f32_16x16x32_bf16 v[38:41], v[146:149], v[206:209], v[38:41]
	v_mfma_f32_16x16x32_bf16 v[22:25], v[146:149], v[232:235], v[22:25]
	v_mfma_f32_16x16x32_bf16 v[58:61], v[154:157], v[190:193], v[58:61]
	v_mfma_f32_16x16x32_bf16 v[46:49], v[154:157], v[198:201], v[46:49]
	v_mfma_f32_16x16x32_bf16 v[30:33], v[154:157], v[206:209], v[30:33]
	v_mfma_f32_16x16x32_bf16 v[14:17], v[154:157], v[232:235], v[14:17]
	v_mfma_f32_16x16x32_bf16 v[62:65], v[150:153], v[194:197], v[62:65]
	v_mfma_f32_16x16x32_bf16 v[54:57], v[150:153], v[202:205], v[54:57]
	v_mfma_f32_16x16x32_bf16 v[38:41], v[150:153], v[228:231], v[38:41]
	v_mfma_f32_16x16x32_bf16 v[22:25], v[150:153], v[236:239], v[22:25]
	v_mfma_f32_16x16x32_bf16 v[58:61], v[158:161], v[194:197], v[58:61]
	v_mfma_f32_16x16x32_bf16 v[46:49], v[158:161], v[202:205], v[46:49]
	v_mfma_f32_16x16x32_bf16 v[30:33], v[158:161], v[228:231], v[30:33]
	v_mfma_f32_16x16x32_bf16 v[14:17], v[158:161], v[236:239], v[14:17]
	s_setprio 0
	s_setprio 1
	v_mfma_f32_16x16x32_bf16 v[50:53], v[162:165], v[190:193], v[50:53]
	v_mfma_f32_16x16x32_bf16 v[34:37], v[162:165], v[198:201], v[34:37]
	v_mfma_f32_16x16x32_bf16 v[18:21], v[162:165], v[206:209], v[18:21]
	v_mfma_f32_16x16x32_bf16 v[6:9], v[162:165], v[232:235], v[6:9]
	v_mfma_f32_16x16x32_bf16 v[42:45], v[170:173], v[190:193], v[42:45]
	v_mfma_f32_16x16x32_bf16 v[26:29], v[170:173], v[198:201], v[26:29]
	v_mfma_f32_16x16x32_bf16 v[10:13], v[170:173], v[206:209], v[10:13]
	v_mfma_f32_16x16x32_bf16 v[2:5], v[170:173], v[232:235], v[2:5]
	v_mfma_f32_16x16x32_bf16 v[50:53], v[166:169], v[194:197], v[50:53]
	v_mfma_f32_16x16x32_bf16 v[34:37], v[166:169], v[202:205], v[34:37]
	v_mfma_f32_16x16x32_bf16 v[18:21], v[166:169], v[228:231], v[18:21]
	v_mfma_f32_16x16x32_bf16 v[6:9], v[166:169], v[236:239], v[6:9]
	v_mfma_f32_16x16x32_bf16 v[42:45], v[178:181], v[194:197], v[42:45]
	v_mfma_f32_16x16x32_bf16 v[26:29], v[178:181], v[202:205], v[26:29]
	v_mfma_f32_16x16x32_bf16 v[10:13], v[178:181], v[228:231], v[10:13]
	v_mfma_f32_16x16x32_bf16 v[2:5], v[178:181], v[236:239], v[2:5]
	s_setprio 0
	s_barrier
	s_add_i32 s48, s48, 2
	s_add_u32 s46, s46, 0x100
	s_addc_u32 s47, s47, 0
	s_cmpk_gt_u32 s48, 0xa9
	s_mov_b64 s[14:15], s[16:17]
	s_cbranch_scc0 .LBB0_805
	s_and_b64 vcc, exec, s[6:7]
	s_cbranch_vccz .LBB0_808
	s_barrier
